# SwiGLU and ProjGate epilogues compute the row rstd values once per phase per workgroup (row block is the same for all its tiles) instead of once per tile
# speedup vs baseline: 1.0133x; 1.0107x over previous
; #define PG8_STAGE(bufoff, gbase, voff) do { _Pragma("unroll") for (int _i = 0; _i < 2; ++_i) \
;         __builtin_amdgcn_global_load_lds((const unsigned*)((const char*)(gbase) + (voff)[_i]), (PG8_LAS unsigned*)(lds + (bufoff) + ldsw + _i * 8192), 16, 0, 0); } while (0)
; #define PG8_WAIT_V(n) asm volatile("s_waitcnt vmcnt(" #n ")" ::: "memory")
; #define PG8_BAR __builtin_amdgcn_s_barrier()
; template <class Epi, class Sched, bool ALIGN_EPI = false, bool SP2 = false>
; __device__ __forceinline__ void gemm_phase(PG8_LAS unsigned char* lds, const Gemm g, const Sched& S, const Epi& E) {
;     ...
;     for (int i = 0; i < 2; ++i) { int R, C; stage_rc(tid * 16 + i * 8192, R, C); const int Rb = Epi::PERM ? ((R & ~31) + perm32(R & 31)) : R;
;         voffA[i] = (unsigned)(R * K + C) * 2u; voffB[i] = (unsigned)(Rb * K + C) * 2u; }
;     const size_t kstep = (size_t)(BK * 2);
;     const size_t hstep = (size_t)HALF * K * 2;
;     const size_t tstep = 2 * hstep;
;     const unsigned ldsw = (unsigned)wid * 1024u;
;     const int aoff = lds_byte(wr * 64 + fr, fq * 8), boff = lds_byte(wc * 32 + fr, fq * 8);
;     ...
;     const char* cA = (const char*)g.A + (size_t)cur.pm * tstep; const char* cB = (const char*)g.Bt + (size_t)cur.pn * tstep;
;     S.a_ready(cur);
;     if constexpr (SP2) {
;         PG8_STAGE(PG8_SB(0, 0), cB, voffB); PG8_STAGE(PG8_SB(0, 1), cB + hstep, voffB); PG8_STAGE(PG8_SA(0, 0), cA, voffA); PG8_STAGE(PG8_SA(0, 1), cA + hstep, voffA);
;         if (wr == 1) PG8_BAR;
;         PG8_WAIT_V(2); PG8_BAR;
;         PG8_STAGE(PG8_SB(1, 0), cB + kstep, voffB); PG8_STAGE(PG8_SA(1, 0), cA + kstep, voffA); PG8_STAGE(PG8_SB(1, 1), cB + hstep + kstep, voffB);
;         PG8_WAIT_V(6); PG8_BAR;
.LBB0_177:
	v_readlane_b32 s12, v255, 9
	v_readlane_b32 s13, v255, 10
	s_mov_b32 s14, s12
	s_mul_hi_i32 s13, s12, 0x3000
	s_mulk_i32 s12, 0x3000
	s_add_u32 s12, s80, s12
	s_mul_i32 s14, s14, 3
	s_addc_u32 s13, s81, s13
	s_ashr_i32 s15, s14, 31
	s_lshl_b64 s[14:15], s[14:15], 20
	v_readlane_b32 s18, v252, 8
	v_readlane_b32 s19, v252, 9
	s_add_u32 s14, s18, s14
	s_addc_u32 s15, s19, s15
	v_lshrrev_b32_e32 v16, 1, v10
	s_add_u32 s14, s14, 0x100000
	v_and_b32_e32 v16, 24, v16
	v_readlane_b32 s22, v254, 11
	s_addc_u32 s15, s15, 0
	v_and_b32_e32 v11, 15, v10
	v_lshlrev_b32_e32 v17, 1, v16
	v_lshlrev_b32_e32 v10, 2, v10
	s_lshl_b32 s1, s1, 5
	v_mov_b32_e32 v153, v197
	v_readlane_b32 s23, v254, 12
	v_lshl_or_b32 v35, s16, 6, v11
	v_lshl_or_b32 v11, v11, 6, v17
	s_lshl_b32 s16, s16, 13
	v_and_b32_e32 v10, 32, v10
	s_and_b32 s1, s1, 0x60
	s_add_i32 m0, s50, 0x18000
	v_lshl_add_u64 v[0:1], v[0:1], 0, s[36:37]
	v_lshl_add_u64 v[12:13], s[22:23], 0, v[152:153]
	v_mov_b32_e32 v149, v197
	v_bitop3_b32 v17, v11, s16, v10 bitop3:0xde
	s_lshl_b32 s16, s1, 7
	s_waitcnt vmcnt(2)
	s_barrier
	global_load_lds_dwordx4 v[0:1], off
	v_lshl_add_u64 v[0:1], v[2:3], 0, s[36:37]
	s_add_i32 m0, s50, 0x1a000
	s_add_i32 s54, s50, 0x8000
	s_add_i32 s55, s50, 0xa000
	v_lshl_add_u64 v[14:15], s[22:23], 0, v[148:149]
	v_bitop3_b32 v170, v11, s16, v10 bitop3:0xde
	global_load_lds_dwordx4 v[0:1], off
	v_lshl_add_u64 v[0:1], v[12:13], 0, s[36:37]
	s_mov_b32 m0, s54
	s_add_u32 s16, s4, 0x40080
	global_load_lds_dwordx4 v[0:1], off
	v_lshl_add_u64 v[0:1], v[14:15], 0, s[36:37]
	s_mov_b32 m0, s55
	s_addc_u32 s17, s5, 0
	global_load_lds_dwordx4 v[0:1], off
	s_add_i32 m0, s50, 0x1c000
	v_lshl_add_u64 v[0:1], s[16:17], 0, v[150:151]
	global_load_lds_dwordx4 v[0:1], off
	v_lshl_add_u64 v[0:1], s[16:17], 0, v[32:33]
	s_add_i32 m0, s50, 0x1e000
	v_or_b32_e32 v171, s1, v16
	global_load_lds_dwordx4 v[0:1], off
	v_lshlrev_b32_e32 v0, 14, v8
	v_and_b32_e32 v0, 0xffff8000, v0
	v_lshl_add_u32 v0, v7, 11, v0
	v_and_b32_e32 v1, 1, v8
	v_lshl_or_b32 v0, v1, 6, v0
	v_lshl_add_u32 v154, v9, 1, v0
	v_lshlrev_b32_e32 v0, 14, v4
	v_and_b32_e32 v0, 0xffff8000, v0
	s_waitcnt vmcnt(6)
	s_cmpk_lt_u32 s0, 0x100
	v_lshl_add_u32 v0, v5, 11, v0
	v_and_b32_e32 v1, 1, v4
	v_readlane_b32 s0, v254, 9
	v_lshl_or_b32 v0, v1, 6, v0
	v_readlane_b32 s1, v254, 10
	v_or_b32_e32 v172, 0xfffff100, v171
	s_cselect_b64 s[16:17], -1, 0
	v_mov_b32_e32 v155, v197
	v_lshl_add_u32 v156, v6, 1, v0
	v_mov_b32_e32 v157, v197
	s_mov_b32 s56, 0
	v_add_u32_e32 v173, 0, v17
	v_readlane_b32 s57, v253, 56
	s_mov_b32 s44, s0
	s_mov_b64 s[0:1], s[22:23]
	s_barrier
	v_mov_b32_e32 v241, -1
	s_branch .LBB0_339

; __device__ __forceinline__ float rstd_of(const float* ssq, int row) {
;     const f32x4* q = (const f32x4*)(ssq + (size_t)row * 16); const f32x4 a = q[0], b = q[1], c = q[2], d = q[3];
;     const float t = (((a.x + a.y) + (a.z + a.w)) + ((b.x + b.y) + (b.z + b.w))) + (((c.x + c.y) + (c.z + c.w)) + ((d.x + d.y) + (d.z + d.w)));
;     return 1.0f / sqrtf(t * (1.0f / DM) + 1e-6f); }
;     __device__ __forceinline__ void operator()(const pg8::f32x4 (&acc)[2][2][4][2], const pg8::Unit& u, int wr, int wc, int fr, int fq) const {
;     ...
;             for (int ai = 0; ai < 2; ++ai)
; #pragma unroll
;                 for (int m = 0; m < 4; ++m) {
;                     const int row = row0 + ai * 128 + m * 16; const float rs = rstd_of(ssq, row);
.LBB0_345:
	v_lshl_add_u32 v158, s44, 8, v35
	v_lshrrev_b32_e32 v220, 2, v158
	v_lshrrev_b32_e32 v221, 3, v158
	v_xor_b32_e32 v220, v220, v221
	v_and_b32_e32 v220, 1, v220
	v_mul_u32_u24_e32 v220, 12, v220
	v_xor_b32_e32 v220, v158, v220
	v_mov_b32_e32 v221, 0
	v_readfirstlane_b32 s100, v241
	s_cmp_eq_u32 s100, s44
	s_cbranch_scc1 .Lrstd_have_pg
	v_mbcnt_lo_u32_b32 v210, -1, 0
	v_mbcnt_hi_u32_b32 v210, -1, v210
	v_lshrrev_b32_e32 v211, 4, v210
	v_and_b32_e32 v212, 1, v211
	v_lshrrev_b32_e32 v211, 1, v211
	v_lshlrev_b32_e32 v212, 5, v212
	v_lshl_add_u32 v212, v211, 7, v212
	v_add_u32_e32 v212, v212, v158
	v_mov_b32_e32 v213, 0
	v_lshlrev_b64 v[212:213], 6, v[212:213]
	v_lshl_add_u64 v[212:213], s[14:15], 0, v[212:213]
	global_load_dwordx4 v[132:135], v[212:213], off
	global_load_dwordx4 v[136:139], v[212:213], off offset:16
	global_load_dwordx4 v[140:143], v[212:213], off offset:32
	global_load_dwordx4 v[144:147], v[212:213], off offset:48
	global_load_dwordx4 v[174:177], v[212:213], off offset:1024
	global_load_dwordx4 v[178:181], v[212:213], off offset:1040
	global_load_dwordx4 v[182:185], v[212:213], off offset:1056
	global_load_dwordx4 v[186:189], v[212:213], off offset:1072
	v_and_b32_e32 v214, 15, v210
	v_lshlrev_b32_e32 v214, 2, v214
	v_add_u32_e32 v215, 64, v214
	v_add_u32_e32 v216, 0x80, v214
	v_add_u32_e32 v217, 0xc0, v214
	s_waitcnt vmcnt(4)
	v_add_f32_e32 v132, v132, v133
	v_add_f32_e32 v134, v134, v135
	v_add_f32_e32 v132, v132, v134
	v_add_f32_e32 v136, v136, v137
	v_add_f32_e32 v138, v138, v139
	v_add_f32_e32 v136, v136, v138
	v_add_f32_e32 v140, v140, v141
	v_add_f32_e32 v142, v142, v143
	v_add_f32_e32 v140, v140, v142
	v_add_f32_e32 v144, v144, v145
	v_add_f32_e32 v146, v146, v147
	v_add_f32_e32 v144, v144, v146
	v_add_f32_e32 v132, v132, v136
	v_add_f32_e32 v140, v140, v144
	v_add_f32_e32 v132, v132, v140
	v_fmamk_f32 v132, v132, 0x3a800000, v229
	v_cmp_gt_f32_e32 vcc, 0xf800000, v132
	v_mul_f32_e32 v137, 0x4f800000, v132
	s_nop 0
	v_cndmask_b32_e32 v132, v132, v137, vcc
	v_sqrt_f32_e32 v137, v132
	s_nop 0
	v_add_u32_e32 v138, -1, v137
	v_fma_f32 v139, -v138, v137, v132
	v_cmp_ge_f32_e64 s[100:101], 0, v139
	v_add_u32_e32 v139, 1, v137
	s_nop 0
	v_cndmask_b32_e64 v138, v137, v138, s[100:101]
	v_fma_f32 v137, -v139, v137, v132
	v_cmp_lt_f32_e64 s[100:101], 0, v137
	s_nop 1
	v_cndmask_b32_e64 v137, v138, v139, s[100:101]
	v_mul_f32_e32 v138, 0x37800000, v137
	v_cndmask_b32_e32 v137, v137, v138, vcc
	v_cmp_class_f32_e32 vcc, v132, v230
	s_nop 1
	v_cndmask_b32_e32 v132, v137, v132, vcc
	v_div_scale_f32 v137, s[100:101], v132, v132, 1.0
	v_rcp_f32_e32 v138, v137
	s_nop 0
	v_fma_f32 v139, -v137, v138, 1.0
	v_fmac_f32_e32 v138, v139, v138
	v_div_scale_f32 v139, vcc, 1.0, v132, 1.0
	v_mul_f32_e32 v141, v139, v138
	v_fma_f32 v142, -v137, v141, v139
	v_fmac_f32_e32 v141, v142, v138
	v_fma_f32 v137, -v137, v141, v139
	v_div_fmas_f32 v137, v137, v138, v141
	v_div_fixup_f32 v218, v137, v132, 1.0
	s_waitcnt vmcnt(0)
	v_add_f32_e32 v174, v174, v175
	v_add_f32_e32 v176, v176, v177
	v_add_f32_e32 v174, v174, v176
	v_add_f32_e32 v178, v178, v179
	v_add_f32_e32 v180, v180, v181
	v_add_f32_e32 v178, v178, v180
	v_add_f32_e32 v182, v182, v183
	v_add_f32_e32 v184, v184, v185
	v_add_f32_e32 v182, v182, v184
	v_add_f32_e32 v186, v186, v187
	v_add_f32_e32 v188, v188, v189
	v_add_f32_e32 v186, v186, v188
	v_add_f32_e32 v174, v174, v178
	v_add_f32_e32 v182, v182, v186
	v_add_f32_e32 v174, v174, v182
	v_fmamk_f32 v174, v174, 0x3a800000, v229
	v_cmp_gt_f32_e32 vcc, 0xf800000, v174
	v_mul_f32_e32 v179, 0x4f800000, v174
	s_nop 0
	v_cndmask_b32_e32 v174, v174, v179, vcc
	v_sqrt_f32_e32 v179, v174
	s_nop 0
	v_add_u32_e32 v180, -1, v179
	v_fma_f32 v181, -v180, v179, v174
	v_cmp_ge_f32_e64 s[100:101], 0, v181
	v_add_u32_e32 v181, 1, v179
	s_nop 0
	v_cndmask_b32_e64 v180, v179, v180, s[100:101]
	v_fma_f32 v179, -v181, v179, v174
	v_cmp_lt_f32_e64 s[100:101], 0, v179
	s_nop 1
	v_cndmask_b32_e64 v179, v180, v181, s[100:101]
	v_mul_f32_e32 v180, 0x37800000, v179
	v_cndmask_b32_e32 v179, v179, v180, vcc
	v_cmp_class_f32_e32 vcc, v174, v230
	s_nop 1
	v_cndmask_b32_e32 v174, v179, v174, vcc
	v_div_scale_f32 v179, s[100:101], v174, v174, 1.0
	v_rcp_f32_e32 v180, v179
	s_nop 0
	v_fma_f32 v181, -v179, v180, 1.0
	v_fmac_f32_e32 v180, v181, v180
	v_div_scale_f32 v181, vcc, 1.0, v174, 1.0
	v_mul_f32_e32 v183, v181, v180
	v_fma_f32 v184, -v179, v183, v181
	v_fmac_f32_e32 v183, v184, v180
	v_fma_f32 v179, -v179, v183, v181
	v_div_fmas_f32 v179, v179, v180, v183
	v_div_fixup_f32 v219, v179, v174, 1.0
	ds_bpermute_b32 v236, v214, v218
	ds_bpermute_b32 v237, v214, v219
	ds_bpermute_b32 v238, v215, v218
	ds_bpermute_b32 v239, v215, v219
	ds_bpermute_b32 v244, v216, v218
	ds_bpermute_b32 v245, v216, v219
	ds_bpermute_b32 v246, v217, v218
	ds_bpermute_b32 v247, v217, v219
	s_waitcnt lgkmcnt(0)
	v_mov_b32_e32 v241, s44
; __device__ __forceinline__ unsigned pk2(float lo, float hi) { return pg8::cvt_pk_bf16(lo, hi); }
; __device__ __forceinline__ float fast_exp2(float x) { return __builtin_amdgcn_exp2f(x); }
; __device__ __forceinline__ float fast_rcp(float x) { return __builtin_amdgcn_rcpf(x); }
;     __device__ __forceinline__ void operator()(const pg8::f32x4 (&acc)[2][2][4][2], const pg8::Unit& u, int wr, int wc, int fr, int fq) const {
;     ...
;         } else {
;             const int col0 = (u.pn - 15) * 256 + wc * 32 + 8 * fq;
;             f32x4 bb[2][2];
; #pragma unroll
;             for (int bj = 0; bj < 2; ++bj) { bb[bj][0] = *(const f32x4*)(bg + col0 + bj * 128); bb[bj][1] = *(const f32x4*)(bg + col0 + bj * 128 + 4); }
; #pragma unroll
;             for (int ai = 0; ai < 2; ++ai)
; #pragma unroll
;                 for (int m = 0; m < 4; ++m) {
;                     const int row = row0 + ai * 128 + m * 16; const float rs = rstd_of(ssq, row);
; #pragma unroll
;                     for (int bj = 0; bj < 2; ++bj) {
;                         float v[8];
; #pragma unroll
;                         for (int j = 0; j < 4; ++j) { v[j] = fast_rcp(1.0f + fast_exp2(-(acc[ai][bj][m][0][j] * rs + bb[bj][0][j]) * LOG2E)); v[4 + j] = fast_rcp(1.0f + fast_exp2(-(acc[ai][bj][m][1][j] * rs + bb[bj][1][j]) * LOG2E)); }
;                         u32x4 w; w.x = pk2(v[0], v[1]); w.y = pk2(v[2], v[3]); w.z = pk2(v[4], v[5]); w.w = pk2(v[6], v[7]);
;                         *(u32x4*)(G + (size_t)row * NGATE + col0 + bj * 128) = w;
;                     }
.Lrstd_have_pg:
	v_or_b32_e32 v164, 16, v158
	v_or_b32_e32 v162, 32, v158
	s_mov_b64 s[0:1], -1
	s_cmp_gt_i32 s57, 14
	v_ashrrev_i32_e32 v159, 31, v158
	v_ashrrev_i32_e32 v165, 31, v164
	v_ashrrev_i32_e32 v163, 31, v162
	v_or_b32_e32 v160, 48, v158
	s_cbranch_scc0 .LBB0_347
	v_lshl_add_u32 v196, s57, 8, v172
	v_lshl_add_u64 v[132:133], v[196:197], 2, s[12:13]
	global_load_dwordx4 v[144:147], v[132:133], off
	global_load_dwordx4 v[140:143], v[132:133], off offset:16
	global_load_dwordx4 v[136:139], v[132:133], off offset:512
	s_nop 0
	global_load_dwordx4 v[132:135], v[132:133], off offset:528
	s_mov_b32 s4, 0xf800000
	v_readlane_b32 s0, v252, 4
	v_readlane_b32 s1, v252, 5
	s_waitcnt vmcnt(0)
	s_nop 0
	v_mov_b64_e32 v[166:167], s[0:1]
	v_mad_i64_i32 v[174:175], s[0:1], v158, s31, v[166:167]
	s_nop 1
	v_lshlrev_b64 v[168:169], 1, v[196:197]
	s_nop 1
	v_lshl_add_u64 v[178:179], v[174:175], 0, v[168:169]
	s_nop 0
	v_mov_b32_e32 v161, v236
	v_fma_f32 v174, v128, v161, v144
	v_fma_f32 v175, v124, v161, v140
	v_fma_f32 v176, v129, v161, v145
	v_fma_f32 v177, v125, v161, v141
	v_fma_f32 v180, v130, v161, v146
	v_fma_f32 v181, v126, v161, v142
	v_fma_f32 v182, v131, v161, v147
	v_fma_f32 v183, v127, v161, v143
	v_mul_f32_e32 v174, 0xbfb8aa3b, v174
	v_mul_f32_e32 v175, 0xbfb8aa3b, v175
	v_mul_f32_e32 v176, 0xbfb8aa3b, v176
	v_mul_f32_e32 v177, 0xbfb8aa3b, v177
	v_mul_f32_e32 v180, 0xbfb8aa3b, v180
	v_mul_f32_e32 v181, 0xbfb8aa3b, v181
	v_mul_f32_e32 v182, 0xbfb8aa3b, v182
	v_mul_f32_e32 v183, 0xbfb8aa3b, v183
	v_exp_f32_e32 v174, v174
	v_exp_f32_e32 v175, v175
	v_exp_f32_e32 v176, v176
	v_exp_f32_e32 v177, v177
	v_exp_f32_e32 v180, v180
	v_exp_f32_e32 v181, v181
	v_exp_f32_e32 v182, v182
	v_exp_f32_e32 v183, v183
	v_add_f32_e32 v174, 1.0, v174
	v_add_f32_e32 v175, 1.0, v175
	v_add_f32_e32 v176, 1.0, v176
	v_add_f32_e32 v177, 1.0, v177
	v_add_f32_e32 v180, 1.0, v180
	v_add_f32_e32 v181, 1.0, v181
	v_add_f32_e32 v182, 1.0, v182
	v_add_f32_e32 v183, 1.0, v183
	v_rcp_f32_e32 v174, v174
	v_rcp_f32_e32 v188, v175
	v_rcp_f32_e32 v175, v176
	v_rcp_f32_e32 v176, v177
	v_rcp_f32_e32 v177, v180
	v_rcp_f32_e32 v180, v181
	v_rcp_f32_e32 v181, v182
	v_rcp_f32_e32 v182, v183
	v_fma_f32 v187, v117, v161, v133
	v_cvt_pk_bf16_f32 v174, v174, v175
	v_cvt_pk_bf16_f32 v175, v177, v181
	v_cvt_pk_bf16_f32 v176, v188, v176
	v_cvt_pk_bf16_f32 v177, v180, v182
	v_mul_f32_e32 v187, 0xbfb8aa3b, v187
	global_store_dwordx4 v[178:179], v[174:177], off
	v_fma_f32 v180, v118, v161, v134
	v_mul_f32_e32 v180, 0xbfb8aa3b, v180
	v_fma_f32 v177, v122, v161, v138
	v_exp_f32_e32 v174, v187
	v_mul_f32_e32 v177, 0xbfb8aa3b, v177
	v_exp_f32_e32 v177, v177
	v_exp_f32_e32 v180, v180
	v_add_f32_e32 v174, 1.0, v174
	v_rcp_f32_e32 v181, v174
	v_add_f32_e32 v174, 1.0, v177
	v_fma_f32 v184, v120, v161, v136
	v_fma_f32 v185, v116, v161, v132
	v_fma_f32 v186, v121, v161, v137
	v_rcp_f32_e32 v177, v174
	v_add_f32_e32 v174, 1.0, v180
	v_fma_f32 v180, v123, v161, v139
	v_fma_f32 v161, v119, v161, v135
	v_mul_f32_e32 v184, 0xbfb8aa3b, v184
	v_mul_f32_e32 v185, 0xbfb8aa3b, v185
	v_mul_f32_e32 v186, 0xbfb8aa3b, v186
	v_mul_f32_e32 v180, 0xbfb8aa3b, v180
	v_mul_f32_e32 v161, 0xbfb8aa3b, v161
	v_exp_f32_e32 v184, v184
	v_exp_f32_e32 v185, v185
	v_exp_f32_e32 v186, v186
	v_exp_f32_e32 v180, v180
	v_exp_f32_e32 v161, v161
	v_add_f32_e32 v184, 1.0, v184
	v_add_f32_e32 v185, 1.0, v185
	v_add_f32_e32 v175, 1.0, v186
	v_rcp_f32_e32 v182, v174
	v_add_f32_e32 v174, 1.0, v180
	v_add_f32_e32 v161, 1.0, v161
	v_rcp_f32_e32 v183, v184
	v_rcp_f32_e32 v176, v185
	v_rcp_f32_e32 v175, v175
	v_rcp_f32_e32 v180, v174
	v_rcp_f32_e32 v161, v161
	v_cvt_pk_bf16_f32 v176, v176, v181
	v_cvt_pk_bf16_f32 v174, v183, v175
	v_cvt_pk_bf16_f32 v175, v177, v180
	v_cvt_pk_bf16_f32 v177, v182, v161
	global_store_dwordx4 v[178:179], v[174:177], off offset:256
	s_nop 1
	v_mov_b32_e32 v161, v237
	v_fma_f32 v175, v108, v161, v140
	v_fma_f32 v176, v113, v161, v145
	v_fma_f32 v177, v109, v161, v141
	v_fma_f32 v178, v114, v161, v146
	v_mul_f32_e32 v175, 0xbfb8aa3b, v175
	v_mul_f32_e32 v176, 0xbfb8aa3b, v176
	v_mul_f32_e32 v177, 0xbfb8aa3b, v177
	v_mul_f32_e32 v178, 0xbfb8aa3b, v178
	v_exp_f32_e32 v175, v175
	v_exp_f32_e32 v176, v176
	v_exp_f32_e32 v177, v177
	v_exp_f32_e32 v178, v178
	v_add_f32_e32 v175, 1.0, v175
	v_add_f32_e32 v176, 1.0, v176
	v_add_f32_e32 v177, 1.0, v177
	v_add_f32_e32 v178, 1.0, v178
	v_fma_f32 v174, v112, v161, v144
	v_fma_f32 v179, v110, v161, v142
	v_fma_f32 v180, v115, v161, v147
	v_rcp_f32_e32 v181, v175
	v_rcp_f32_e32 v175, v176
	v_rcp_f32_e32 v176, v177
	v_rcp_f32_e32 v177, v178
	v_fma_f32 v178, v111, v161, v143
	v_mul_f32_e32 v174, 0xbfb8aa3b, v174
	v_mul_f32_e32 v179, 0xbfb8aa3b, v179
	v_mul_f32_e32 v180, 0xbfb8aa3b, v180
	v_mul_f32_e32 v178, 0xbfb8aa3b, v178
	v_exp_f32_e32 v174, v174
	v_exp_f32_e32 v179, v179
	v_exp_f32_e32 v180, v180
	v_exp_f32_e32 v178, v178
	v_add_f32_e32 v174, 1.0, v174
	v_add_f32_e32 v179, 1.0, v179
	v_add_f32_e32 v180, 1.0, v180
	v_add_f32_e32 v178, 1.0, v178
	v_rcp_f32_e32 v174, v174
	v_rcp_f32_e32 v179, v179
	v_rcp_f32_e32 v180, v180
	v_rcp_f32_e32 v178, v178
	v_cvt_pk_bf16_f32 v174, v174, v175
	v_cvt_pk_bf16_f32 v176, v181, v176
	v_cvt_pk_bf16_f32 v175, v177, v180
	v_cvt_pk_bf16_f32 v177, v179, v178
	v_mad_i64_i32 v[178:179], s[0:1], v164, s31, v[166:167]
	v_lshl_add_u64 v[178:179], v[178:179], 0, v[168:169]
	v_fma_f32 v181, v100, v161, v132
	v_fma_f32 v180, v104, v161, v136
	v_mul_f32_e32 v181, 0xbfb8aa3b, v181
	global_store_dwordx4 v[178:179], v[174:177], off
	v_mul_f32_e32 v180, 0xbfb8aa3b, v180
	v_exp_f32_e32 v181, v181
	v_fma_f32 v176, v105, v161, v137
	v_fma_f32 v177, v101, v161, v133
; __device__ __forceinline__ unsigned pk2(float lo, float hi) { return pg8::cvt_pk_bf16(lo, hi); }
; __device__ __forceinline__ float fast_exp2(float x) { return __builtin_amdgcn_exp2f(x); }
; __device__ __forceinline__ float fast_rcp(float x) { return __builtin_amdgcn_rcpf(x); }
;     __device__ __forceinline__ void operator()(const pg8::f32x4 (&acc)[2][2][4][2], const pg8::Unit& u, int wr, int wc, int fr, int fq) const {
;     ...
;             for (int ai = 0; ai < 2; ++ai)
; #pragma unroll
;                 for (int m = 0; m < 4; ++m) {
;                     const int row = row0 + ai * 128 + m * 16; const float rs = rstd_of(ssq, row);
; #pragma unroll
;                     for (int bj = 0; bj < 2; ++bj) {
;                         float v[8];
; #pragma unroll
;                         for (int j = 0; j < 4; ++j) { v[j] = fast_rcp(1.0f + fast_exp2(-(acc[ai][bj][m][0][j] * rs + bb[bj][0][j]) * LOG2E)); v[4 + j] = fast_rcp(1.0f + fast_exp2(-(acc[ai][bj][m][1][j] * rs + bb[bj][1][j]) * LOG2E)); }
;                         u32x4 w; w.x = pk2(v[0], v[1]); w.y = pk2(v[2], v[3]); w.z = pk2(v[4], v[5]); w.w = pk2(v[6], v[7]);
;                         *(u32x4*)(G + (size_t)row * NGATE + col0 + bj * 128) = w;
;                     }
	v_mul_f32_e32 v176, 0xbfb8aa3b, v176
	v_mul_f32_e32 v177, 0xbfb8aa3b, v177
	v_exp_f32_e32 v180, v180
	v_exp_f32_e32 v176, v176
	v_exp_f32_e32 v177, v177
	v_add_f32_e32 v175, 1.0, v181
	v_add_f32_e32 v174, 1.0, v180
	v_rcp_f32_e32 v180, v175
	v_add_f32_e32 v175, 1.0, v176
	v_add_f32_e32 v176, 1.0, v177
	v_fma_f32 v177, v106, v161, v138
	v_fma_f32 v181, v102, v161, v134
	v_fma_f32 v182, v107, v161, v139
	v_fma_f32 v161, v103, v161, v135
	v_mul_f32_e32 v177, 0xbfb8aa3b, v177
	v_mul_f32_e32 v181, 0xbfb8aa3b, v181
	v_mul_f32_e32 v182, 0xbfb8aa3b, v182
	v_mul_f32_e32 v161, 0xbfb8aa3b, v161
	v_exp_f32_e32 v177, v177
	v_exp_f32_e32 v181, v181
	v_exp_f32_e32 v182, v182
	v_exp_f32_e32 v161, v161
	v_add_f32_e32 v177, 1.0, v177
	v_add_f32_e32 v181, 1.0, v181
	v_add_f32_e32 v182, 1.0, v182
	v_add_f32_e32 v161, 1.0, v161
	v_rcp_f32_e32 v174, v174
	v_rcp_f32_e32 v175, v175
	v_rcp_f32_e32 v176, v176
	v_rcp_f32_e32 v177, v177
	v_rcp_f32_e32 v181, v181
	v_rcp_f32_e32 v182, v182
	v_rcp_f32_e32 v161, v161
	v_cvt_pk_bf16_f32 v174, v174, v175
	v_cvt_pk_bf16_f32 v176, v180, v176
	v_cvt_pk_bf16_f32 v175, v177, v182
	v_cvt_pk_bf16_f32 v177, v181, v161
	global_store_dwordx4 v[178:179], v[174:177], off offset:256
	s_nop 1
	v_mov_b32_e32 v161, v238
	v_fma_f32 v175, v92, v161, v140
	v_mul_f32_e32 v175, 0xbfb8aa3b, v175
	v_fma_f32 v176, v97, v161, v145
	v_fma_f32 v177, v93, v161, v141
	v_exp_f32_e32 v175, v175
	v_mul_f32_e32 v176, 0xbfb8aa3b, v176
	v_mul_f32_e32 v177, 0xbfb8aa3b, v177
	v_exp_f32_e32 v176, v176
	v_exp_f32_e32 v177, v177
	v_add_f32_e32 v175, 1.0, v175
	v_fma_f32 v174, v96, v161, v144
	v_rcp_f32_e32 v178, v175
	v_add_f32_e32 v175, 1.0, v176
	v_add_f32_e32 v176, 1.0, v177
	v_fma_f32 v177, v98, v161, v146
	v_fma_f32 v179, v94, v161, v142
	v_fma_f32 v180, v99, v161, v147
	v_fma_f32 v181, v95, v161, v143
	v_mul_f32_e32 v174, 0xbfb8aa3b, v174
	v_mul_f32_e32 v177, 0xbfb8aa3b, v177
	v_mul_f32_e32 v179, 0xbfb8aa3b, v179
	v_mul_f32_e32 v180, 0xbfb8aa3b, v180
	v_mul_f32_e32 v181, 0xbfb8aa3b, v181
	v_exp_f32_e32 v174, v174
	v_exp_f32_e32 v177, v177
	v_exp_f32_e32 v179, v179
	v_exp_f32_e32 v180, v180
	v_exp_f32_e32 v181, v181
	v_add_f32_e32 v174, 1.0, v174
	v_add_f32_e32 v177, 1.0, v177
	v_add_f32_e32 v179, 1.0, v179
	v_add_f32_e32 v180, 1.0, v180
	v_add_f32_e32 v181, 1.0, v181
	v_rcp_f32_e32 v174, v174
	v_rcp_f32_e32 v175, v175
	v_rcp_f32_e32 v176, v176
	v_rcp_f32_e32 v177, v177
	v_rcp_f32_e32 v179, v179
	v_rcp_f32_e32 v180, v180
	v_rcp_f32_e32 v181, v181
	v_cvt_pk_bf16_f32 v174, v174, v175
	v_cvt_pk_bf16_f32 v176, v178, v176
	v_cvt_pk_bf16_f32 v175, v177, v180
	v_cvt_pk_bf16_f32 v177, v179, v181
	v_mad_i64_i32 v[178:179], s[0:1], v162, s31, v[166:167]
	v_lshl_add_u64 v[178:179], v[178:179], 0, v[168:169]
	v_fma_f32 v181, v84, v161, v132
	v_fma_f32 v180, v88, v161, v136
	v_mul_f32_e32 v181, 0xbfb8aa3b, v181
	global_store_dwordx4 v[178:179], v[174:177], off
	v_mul_f32_e32 v180, 0xbfb8aa3b, v180
	v_exp_f32_e32 v181, v181
	v_fma_f32 v176, v89, v161, v137
	v_fma_f32 v177, v85, v161, v133
	v_mul_f32_e32 v176, 0xbfb8aa3b, v176
	v_mul_f32_e32 v177, 0xbfb8aa3b, v177
	v_exp_f32_e32 v180, v180
	v_exp_f32_e32 v176, v176
	v_exp_f32_e32 v177, v177
	v_add_f32_e32 v175, 1.0, v181
	v_add_f32_e32 v174, 1.0, v180
	v_rcp_f32_e32 v180, v175
	v_add_f32_e32 v175, 1.0, v176
	v_add_f32_e32 v176, 1.0, v177
	v_fma_f32 v177, v90, v161, v138
	v_fma_f32 v181, v86, v161, v134
	v_fma_f32 v182, v91, v161, v139
	v_fma_f32 v161, v87, v161, v135
	v_mul_f32_e32 v177, 0xbfb8aa3b, v177
	v_mul_f32_e32 v181, 0xbfb8aa3b, v181
	v_mul_f32_e32 v182, 0xbfb8aa3b, v182
	v_mul_f32_e32 v161, 0xbfb8aa3b, v161
	v_exp_f32_e32 v177, v177
	v_exp_f32_e32 v181, v181
	v_exp_f32_e32 v182, v182
	v_exp_f32_e32 v161, v161
	v_add_f32_e32 v177, 1.0, v177
	v_add_f32_e32 v181, 1.0, v181
	v_add_f32_e32 v182, 1.0, v182
	v_add_f32_e32 v161, 1.0, v161
	v_rcp_f32_e32 v174, v174
	v_rcp_f32_e32 v175, v175
	v_rcp_f32_e32 v176, v176
	v_rcp_f32_e32 v177, v177
	v_rcp_f32_e32 v181, v181
	v_rcp_f32_e32 v182, v182
	v_rcp_f32_e32 v161, v161
	v_cvt_pk_bf16_f32 v174, v174, v175
	v_cvt_pk_bf16_f32 v176, v180, v176
	v_cvt_pk_bf16_f32 v175, v177, v182
	v_cvt_pk_bf16_f32 v177, v181, v161
	global_store_dwordx4 v[178:179], v[174:177], off offset:256
	s_nop 1
	v_add_u32_e32 v190, 0x80, v158
	v_ashrrev_i32_e32 v191, 31, v190
	s_nop 1
	v_mov_b32_e32 v161, v239
	v_fma_f32 v175, v76, v161, v140
	v_mul_f32_e32 v175, 0xbfb8aa3b, v175
	v_fma_f32 v176, v81, v161, v145
	v_fma_f32 v177, v77, v161, v141
	v_exp_f32_e32 v175, v175
	v_mul_f32_e32 v176, 0xbfb8aa3b, v176
	v_mul_f32_e32 v177, 0xbfb8aa3b, v177
	v_exp_f32_e32 v176, v176
	v_exp_f32_e32 v177, v177
	v_add_f32_e32 v175, 1.0, v175
	v_fma_f32 v174, v80, v161, v144
	v_rcp_f32_e32 v178, v175
	v_add_f32_e32 v175, 1.0, v176
	v_add_f32_e32 v176, 1.0, v177
	v_fma_f32 v177, v82, v161, v146
	v_fma_f32 v179, v78, v161, v142
	v_fma_f32 v180, v83, v161, v147
	v_fma_f32 v181, v79, v161, v143
	v_mul_f32_e32 v174, 0xbfb8aa3b, v174
	v_mul_f32_e32 v177, 0xbfb8aa3b, v177
	v_mul_f32_e32 v179, 0xbfb8aa3b, v179
	v_mul_f32_e32 v180, 0xbfb8aa3b, v180
	v_mul_f32_e32 v181, 0xbfb8aa3b, v181
	v_exp_f32_e32 v174, v174
	v_exp_f32_e32 v177, v177
	v_exp_f32_e32 v179, v179
	v_exp_f32_e32 v180, v180
	v_exp_f32_e32 v181, v181
	v_add_f32_e32 v174, 1.0, v174
	v_add_f32_e32 v177, 1.0, v177
	v_add_f32_e32 v179, 1.0, v179
	v_add_f32_e32 v180, 1.0, v180
	v_add_f32_e32 v181, 1.0, v181
	v_rcp_f32_e32 v174, v174
	v_rcp_f32_e32 v175, v175
	v_rcp_f32_e32 v176, v176
	v_rcp_f32_e32 v177, v177
	v_rcp_f32_e32 v179, v179
	v_rcp_f32_e32 v180, v180
	v_rcp_f32_e32 v181, v181
	v_cvt_pk_bf16_f32 v174, v174, v175
	v_cvt_pk_bf16_f32 v176, v178, v176
; __device__ __forceinline__ unsigned pk2(float lo, float hi) { return pg8::cvt_pk_bf16(lo, hi); }
; __device__ __forceinline__ float fast_exp2(float x) { return __builtin_amdgcn_exp2f(x); }
; __device__ __forceinline__ float fast_rcp(float x) { return __builtin_amdgcn_rcpf(x); }
;     __device__ __forceinline__ void operator()(const pg8::f32x4 (&acc)[2][2][4][2], const pg8::Unit& u, int wr, int wc, int fr, int fq) const {
;     ...
;             for (int ai = 0; ai < 2; ++ai)
; #pragma unroll
;                 for (int m = 0; m < 4; ++m) {
;                     const int row = row0 + ai * 128 + m * 16; const float rs = rstd_of(ssq, row);
; #pragma unroll
;                     for (int bj = 0; bj < 2; ++bj) {
;                         float v[8];
; #pragma unroll
;                         for (int j = 0; j < 4; ++j) { v[j] = fast_rcp(1.0f + fast_exp2(-(acc[ai][bj][m][0][j] * rs + bb[bj][0][j]) * LOG2E)); v[4 + j] = fast_rcp(1.0f + fast_exp2(-(acc[ai][bj][m][1][j] * rs + bb[bj][1][j]) * LOG2E)); }
;                         u32x4 w; w.x = pk2(v[0], v[1]); w.y = pk2(v[2], v[3]); w.z = pk2(v[4], v[5]); w.w = pk2(v[6], v[7]);
;                         *(u32x4*)(G + (size_t)row * NGATE + col0 + bj * 128) = w;
;                     }
	v_cvt_pk_bf16_f32 v175, v177, v180
	v_cvt_pk_bf16_f32 v177, v179, v181
	v_mad_i64_i32 v[178:179], s[0:1], v160, s31, v[166:167]
	v_lshl_add_u64 v[178:179], v[178:179], 0, v[168:169]
	v_fma_f32 v181, v68, v161, v132
	v_fma_f32 v180, v72, v161, v136
	v_mul_f32_e32 v181, 0xbfb8aa3b, v181
	global_store_dwordx4 v[178:179], v[174:177], off
	v_mul_f32_e32 v180, 0xbfb8aa3b, v180
	v_exp_f32_e32 v181, v181
	v_fma_f32 v176, v73, v161, v137
	v_fma_f32 v177, v69, v161, v133
	v_mul_f32_e32 v176, 0xbfb8aa3b, v176
	v_mul_f32_e32 v177, 0xbfb8aa3b, v177
	v_exp_f32_e32 v180, v180
	v_exp_f32_e32 v176, v176
	v_exp_f32_e32 v177, v177
	v_add_f32_e32 v175, 1.0, v181
	v_add_f32_e32 v174, 1.0, v180
	v_rcp_f32_e32 v180, v175
	v_add_f32_e32 v175, 1.0, v176
	v_add_f32_e32 v176, 1.0, v177
	v_fma_f32 v177, v74, v161, v138
	v_fma_f32 v181, v70, v161, v134
	v_fma_f32 v182, v75, v161, v139
	v_fma_f32 v161, v71, v161, v135
	v_mul_f32_e32 v177, 0xbfb8aa3b, v177
	v_mul_f32_e32 v181, 0xbfb8aa3b, v181
	v_mul_f32_e32 v182, 0xbfb8aa3b, v182
	v_mul_f32_e32 v161, 0xbfb8aa3b, v161
	v_exp_f32_e32 v177, v177
	v_exp_f32_e32 v181, v181
	v_exp_f32_e32 v182, v182
	v_exp_f32_e32 v161, v161
	v_add_f32_e32 v177, 1.0, v177
	v_add_f32_e32 v181, 1.0, v181
	v_add_f32_e32 v182, 1.0, v182
	v_add_f32_e32 v161, 1.0, v161
	v_rcp_f32_e32 v174, v174
	v_rcp_f32_e32 v175, v175
	v_rcp_f32_e32 v176, v176
	v_rcp_f32_e32 v177, v177
	v_rcp_f32_e32 v181, v181
	v_rcp_f32_e32 v182, v182
	v_rcp_f32_e32 v161, v161
	v_cvt_pk_bf16_f32 v174, v174, v175
	v_cvt_pk_bf16_f32 v176, v180, v176
	v_cvt_pk_bf16_f32 v175, v177, v182
	v_cvt_pk_bf16_f32 v177, v181, v161
	global_store_dwordx4 v[178:179], v[174:177], off offset:256
	s_nop 1
	v_mov_b32_e32 v161, v244
	v_fma_f32 v175, v60, v161, v140
	v_mul_f32_e32 v175, 0xbfb8aa3b, v175
	v_fma_f32 v176, v65, v161, v145
	v_fma_f32 v177, v61, v161, v141
	v_exp_f32_e32 v175, v175
	v_mul_f32_e32 v176, 0xbfb8aa3b, v176
	v_mul_f32_e32 v177, 0xbfb8aa3b, v177
	v_exp_f32_e32 v176, v176
	v_exp_f32_e32 v177, v177
	v_add_f32_e32 v175, 1.0, v175
	v_fma_f32 v174, v64, v161, v144
	v_rcp_f32_e32 v178, v175
	v_add_f32_e32 v175, 1.0, v176
	v_add_f32_e32 v176, 1.0, v177
	v_fma_f32 v177, v66, v161, v146
	v_fma_f32 v179, v62, v161, v142
	v_fma_f32 v180, v67, v161, v147
	v_fma_f32 v181, v63, v161, v143
	v_mul_f32_e32 v174, 0xbfb8aa3b, v174
	v_mul_f32_e32 v177, 0xbfb8aa3b, v177
	v_mul_f32_e32 v179, 0xbfb8aa3b, v179
	v_mul_f32_e32 v180, 0xbfb8aa3b, v180
	v_mul_f32_e32 v181, 0xbfb8aa3b, v181
	v_exp_f32_e32 v174, v174
	v_exp_f32_e32 v177, v177
	v_exp_f32_e32 v179, v179
	v_exp_f32_e32 v180, v180
	v_exp_f32_e32 v181, v181
	v_add_f32_e32 v174, 1.0, v174
	v_add_f32_e32 v177, 1.0, v177
	v_add_f32_e32 v179, 1.0, v179
	v_add_f32_e32 v180, 1.0, v180
	v_add_f32_e32 v181, 1.0, v181
	v_rcp_f32_e32 v174, v174
	v_rcp_f32_e32 v175, v175
	v_rcp_f32_e32 v176, v176
	v_rcp_f32_e32 v177, v177
	v_rcp_f32_e32 v179, v179
	v_rcp_f32_e32 v180, v180
	v_rcp_f32_e32 v181, v181
	v_cvt_pk_bf16_f32 v174, v174, v175
	v_cvt_pk_bf16_f32 v176, v178, v176
	v_cvt_pk_bf16_f32 v175, v177, v180
	v_cvt_pk_bf16_f32 v177, v179, v181
	v_mad_i64_i32 v[178:179], s[0:1], v190, s31, v[166:167]
	v_lshl_add_u64 v[178:179], v[178:179], 0, v[168:169]
	v_fma_f32 v181, v52, v161, v132
	v_fma_f32 v180, v56, v161, v136
	v_mul_f32_e32 v181, 0xbfb8aa3b, v181
	global_store_dwordx4 v[178:179], v[174:177], off
	v_mul_f32_e32 v180, 0xbfb8aa3b, v180
	v_exp_f32_e32 v181, v181
	v_fma_f32 v176, v57, v161, v137
	v_fma_f32 v177, v53, v161, v133
	v_mul_f32_e32 v176, 0xbfb8aa3b, v176
	v_mul_f32_e32 v177, 0xbfb8aa3b, v177
	v_exp_f32_e32 v180, v180
	v_exp_f32_e32 v176, v176
	v_exp_f32_e32 v177, v177
	v_add_f32_e32 v175, 1.0, v181
	v_add_f32_e32 v174, 1.0, v180
	v_rcp_f32_e32 v180, v175
	v_add_f32_e32 v175, 1.0, v176
	v_add_f32_e32 v176, 1.0, v177
	v_fma_f32 v177, v58, v161, v138
	v_fma_f32 v181, v54, v161, v134
	v_fma_f32 v182, v59, v161, v139
	v_fma_f32 v161, v55, v161, v135
	v_mul_f32_e32 v177, 0xbfb8aa3b, v177
	v_mul_f32_e32 v181, 0xbfb8aa3b, v181
	v_mul_f32_e32 v182, 0xbfb8aa3b, v182
	v_mul_f32_e32 v161, 0xbfb8aa3b, v161
	v_exp_f32_e32 v177, v177
	v_exp_f32_e32 v181, v181
	v_exp_f32_e32 v182, v182
	v_exp_f32_e32 v161, v161
	v_add_f32_e32 v177, 1.0, v177
	v_add_f32_e32 v181, 1.0, v181
	v_add_f32_e32 v182, 1.0, v182
	v_add_f32_e32 v161, 1.0, v161
	v_rcp_f32_e32 v174, v174
	v_rcp_f32_e32 v175, v175
	v_rcp_f32_e32 v176, v176
	v_rcp_f32_e32 v177, v177
	v_rcp_f32_e32 v181, v181
	v_rcp_f32_e32 v182, v182
	v_rcp_f32_e32 v161, v161
	v_add_u32_e32 v190, 0x90, v158
	v_cvt_pk_bf16_f32 v174, v174, v175
	v_cvt_pk_bf16_f32 v175, v177, v182
	v_cvt_pk_bf16_f32 v176, v180, v176
	v_cvt_pk_bf16_f32 v177, v181, v161
	global_store_dwordx4 v[178:179], v[174:177], off offset:256
	s_nop 1
	v_mov_b32_e32 v161, v245
	v_fma_f32 v175, v44, v161, v140
	v_mul_f32_e32 v175, 0xbfb8aa3b, v175
	v_fma_f32 v176, v49, v161, v145
	v_fma_f32 v177, v45, v161, v141
	v_exp_f32_e32 v175, v175
	v_mul_f32_e32 v176, 0xbfb8aa3b, v176
	v_mul_f32_e32 v177, 0xbfb8aa3b, v177
	v_exp_f32_e32 v176, v176
	v_exp_f32_e32 v177, v177
	v_add_f32_e32 v175, 1.0, v175
	v_fma_f32 v174, v48, v161, v144
	v_rcp_f32_e32 v178, v175
	v_add_f32_e32 v175, 1.0, v176
	v_add_f32_e32 v176, 1.0, v177
	v_fma_f32 v177, v50, v161, v146
	v_fma_f32 v179, v46, v161, v142
	v_fma_f32 v180, v51, v161, v147
	v_fma_f32 v181, v47, v161, v143
	v_mul_f32_e32 v174, 0xbfb8aa3b, v174
	v_mul_f32_e32 v177, 0xbfb8aa3b, v177
	v_mul_f32_e32 v179, 0xbfb8aa3b, v179
	v_mul_f32_e32 v180, 0xbfb8aa3b, v180
	v_mul_f32_e32 v181, 0xbfb8aa3b, v181
	v_exp_f32_e32 v174, v174
	v_exp_f32_e32 v177, v177
	v_exp_f32_e32 v179, v179
	v_exp_f32_e32 v180, v180
	v_exp_f32_e32 v181, v181
; __device__ __forceinline__ unsigned pk2(float lo, float hi) { return pg8::cvt_pk_bf16(lo, hi); }
; __device__ __forceinline__ float fast_exp2(float x) { return __builtin_amdgcn_exp2f(x); }
; __device__ __forceinline__ float fast_rcp(float x) { return __builtin_amdgcn_rcpf(x); }
;     __device__ __forceinline__ void operator()(const pg8::f32x4 (&acc)[2][2][4][2], const pg8::Unit& u, int wr, int wc, int fr, int fq) const {
;     ...
;             for (int ai = 0; ai < 2; ++ai)
; #pragma unroll
;                 for (int m = 0; m < 4; ++m) {
;                     const int row = row0 + ai * 128 + m * 16; const float rs = rstd_of(ssq, row);
; #pragma unroll
;                     for (int bj = 0; bj < 2; ++bj) {
;                         float v[8];
; #pragma unroll
;                         for (int j = 0; j < 4; ++j) { v[j] = fast_rcp(1.0f + fast_exp2(-(acc[ai][bj][m][0][j] * rs + bb[bj][0][j]) * LOG2E)); v[4 + j] = fast_rcp(1.0f + fast_exp2(-(acc[ai][bj][m][1][j] * rs + bb[bj][1][j]) * LOG2E)); }
;                         u32x4 w; w.x = pk2(v[0], v[1]); w.y = pk2(v[2], v[3]); w.z = pk2(v[4], v[5]); w.w = pk2(v[6], v[7]);
;                         *(u32x4*)(G + (size_t)row * NGATE + col0 + bj * 128) = w;
;                     }
	v_add_f32_e32 v174, 1.0, v174
	v_add_f32_e32 v177, 1.0, v177
	v_add_f32_e32 v179, 1.0, v179
	v_add_f32_e32 v180, 1.0, v180
	v_add_f32_e32 v181, 1.0, v181
	v_rcp_f32_e32 v174, v174
	v_rcp_f32_e32 v175, v175
	v_rcp_f32_e32 v176, v176
	v_rcp_f32_e32 v177, v177
	v_rcp_f32_e32 v179, v179
	v_rcp_f32_e32 v180, v180
	v_rcp_f32_e32 v181, v181
	v_cvt_pk_bf16_f32 v174, v174, v175
	v_cvt_pk_bf16_f32 v176, v178, v176
	v_cvt_pk_bf16_f32 v175, v177, v180
	v_cvt_pk_bf16_f32 v177, v179, v181
	v_mad_i64_i32 v[178:179], s[0:1], v190, s31, v[166:167]
	v_lshl_add_u64 v[178:179], v[178:179], 0, v[168:169]
	v_fma_f32 v181, v36, v161, v132
	v_fma_f32 v180, v40, v161, v136
	v_mul_f32_e32 v181, 0xbfb8aa3b, v181
	global_store_dwordx4 v[178:179], v[174:177], off
	v_mul_f32_e32 v180, 0xbfb8aa3b, v180
	v_exp_f32_e32 v181, v181
	v_fma_f32 v176, v41, v161, v137
	v_fma_f32 v177, v37, v161, v133
	v_mul_f32_e32 v176, 0xbfb8aa3b, v176
	v_mul_f32_e32 v177, 0xbfb8aa3b, v177
	v_exp_f32_e32 v180, v180
	v_exp_f32_e32 v176, v176
	v_exp_f32_e32 v177, v177
	v_add_f32_e32 v175, 1.0, v181
	v_add_f32_e32 v174, 1.0, v180
	v_rcp_f32_e32 v180, v175
	v_add_f32_e32 v175, 1.0, v176
	v_add_f32_e32 v176, 1.0, v177
	v_fma_f32 v177, v42, v161, v138
	v_fma_f32 v181, v38, v161, v134
	v_fma_f32 v182, v43, v161, v139
	v_fma_f32 v161, v39, v161, v135
	v_mul_f32_e32 v177, 0xbfb8aa3b, v177
	v_mul_f32_e32 v181, 0xbfb8aa3b, v181
	v_mul_f32_e32 v182, 0xbfb8aa3b, v182
	v_mul_f32_e32 v161, 0xbfb8aa3b, v161
	v_exp_f32_e32 v177, v177
	v_exp_f32_e32 v181, v181
	v_exp_f32_e32 v182, v182
	v_exp_f32_e32 v161, v161
	v_add_f32_e32 v177, 1.0, v177
	v_add_f32_e32 v181, 1.0, v181
	v_add_f32_e32 v182, 1.0, v182
	v_add_f32_e32 v161, 1.0, v161
	v_rcp_f32_e32 v174, v174
	v_rcp_f32_e32 v175, v175
	v_rcp_f32_e32 v176, v176
	v_rcp_f32_e32 v177, v177
	v_rcp_f32_e32 v181, v181
	v_rcp_f32_e32 v182, v182
	v_rcp_f32_e32 v161, v161
	v_add_u32_e32 v190, 0xa0, v158
	v_cvt_pk_bf16_f32 v174, v174, v175
	v_cvt_pk_bf16_f32 v175, v177, v182
	v_cvt_pk_bf16_f32 v176, v180, v176
	v_cvt_pk_bf16_f32 v177, v181, v161
	global_store_dwordx4 v[178:179], v[174:177], off offset:256
	s_nop 1
	v_mov_b32_e32 v161, v246
	v_fma_f32 v175, v24, v161, v140
	v_mul_f32_e32 v175, 0xbfb8aa3b, v175
	v_fma_f32 v176, v29, v161, v145
	v_fma_f32 v177, v25, v161, v141
	v_exp_f32_e32 v175, v175
	v_mul_f32_e32 v176, 0xbfb8aa3b, v176
	v_mul_f32_e32 v177, 0xbfb8aa3b, v177
	v_exp_f32_e32 v176, v176
	v_exp_f32_e32 v177, v177
	v_add_f32_e32 v175, 1.0, v175
	v_fma_f32 v174, v28, v161, v144
	v_rcp_f32_e32 v178, v175
	v_add_f32_e32 v175, 1.0, v176
	v_add_f32_e32 v176, 1.0, v177
	v_fma_f32 v177, v30, v161, v146
	v_fma_f32 v179, v26, v161, v142
	v_fma_f32 v180, v31, v161, v147
	v_fma_f32 v181, v27, v161, v143
	v_mul_f32_e32 v174, 0xbfb8aa3b, v174
	v_mul_f32_e32 v177, 0xbfb8aa3b, v177
	v_mul_f32_e32 v179, 0xbfb8aa3b, v179
	v_mul_f32_e32 v180, 0xbfb8aa3b, v180
	v_mul_f32_e32 v181, 0xbfb8aa3b, v181
	v_exp_f32_e32 v174, v174
	v_exp_f32_e32 v177, v177
	v_exp_f32_e32 v179, v179
	v_exp_f32_e32 v180, v180
	v_exp_f32_e32 v181, v181
	v_add_f32_e32 v174, 1.0, v174
	v_add_f32_e32 v177, 1.0, v177
	v_add_f32_e32 v179, 1.0, v179
	v_add_f32_e32 v180, 1.0, v180
	v_add_f32_e32 v181, 1.0, v181
	v_rcp_f32_e32 v174, v174
	v_rcp_f32_e32 v175, v175
	v_rcp_f32_e32 v176, v176
	v_rcp_f32_e32 v177, v177
	v_rcp_f32_e32 v179, v179
	v_rcp_f32_e32 v180, v180
	v_rcp_f32_e32 v181, v181
	v_cvt_pk_bf16_f32 v174, v174, v175
	v_cvt_pk_bf16_f32 v176, v178, v176
	v_cvt_pk_bf16_f32 v175, v177, v180
	v_cvt_pk_bf16_f32 v177, v179, v181
	v_mad_i64_i32 v[178:179], s[0:1], v190, s31, v[166:167]
	v_lshl_add_u64 v[178:179], v[178:179], 0, v[168:169]
	v_fma_f32 v181, v16, v161, v132
	v_fma_f32 v180, v20, v161, v136
	v_mul_f32_e32 v181, 0xbfb8aa3b, v181
	global_store_dwordx4 v[178:179], v[174:177], off
	v_mul_f32_e32 v180, 0xbfb8aa3b, v180
	v_exp_f32_e32 v181, v181
	v_fma_f32 v176, v21, v161, v137
	v_fma_f32 v177, v17, v161, v133
	v_mul_f32_e32 v176, 0xbfb8aa3b, v176
	v_mul_f32_e32 v177, 0xbfb8aa3b, v177
	v_exp_f32_e32 v180, v180
	v_exp_f32_e32 v176, v176
	v_exp_f32_e32 v177, v177
; __device__ __forceinline__ unsigned pk2(float lo, float hi) { return pg8::cvt_pk_bf16(lo, hi); }
; __device__ __forceinline__ float fast_exp2(float x) { return __builtin_amdgcn_exp2f(x); }
; __device__ __forceinline__ float fast_rcp(float x) { return __builtin_amdgcn_rcpf(x); }
;     __device__ __forceinline__ void operator()(const pg8::f32x4 (&acc)[2][2][4][2], const pg8::Unit& u, int wr, int wc, int fr, int fq) const {
;     ...
;             for (int ai = 0; ai < 2; ++ai)
; #pragma unroll
;                 for (int m = 0; m < 4; ++m) {
;                     const int row = row0 + ai * 128 + m * 16; const float rs = rstd_of(ssq, row);
; #pragma unroll
;                     for (int bj = 0; bj < 2; ++bj) {
;                         float v[8];
; #pragma unroll
;                         for (int j = 0; j < 4; ++j) { v[j] = fast_rcp(1.0f + fast_exp2(-(acc[ai][bj][m][0][j] * rs + bb[bj][0][j]) * LOG2E)); v[4 + j] = fast_rcp(1.0f + fast_exp2(-(acc[ai][bj][m][1][j] * rs + bb[bj][1][j]) * LOG2E)); }
;                         u32x4 w; w.x = pk2(v[0], v[1]); w.y = pk2(v[2], v[3]); w.z = pk2(v[4], v[5]); w.w = pk2(v[6], v[7]);
;                         *(u32x4*)(G + (size_t)row * NGATE + col0 + bj * 128) = w;
;                     }
	v_add_f32_e32 v175, 1.0, v181
	v_add_f32_e32 v174, 1.0, v180
	v_rcp_f32_e32 v180, v175
	v_add_f32_e32 v175, 1.0, v176
	v_add_f32_e32 v176, 1.0, v177
	v_fma_f32 v177, v22, v161, v138
	v_fma_f32 v181, v18, v161, v134
	v_fma_f32 v182, v23, v161, v139
	v_fma_f32 v161, v19, v161, v135
	v_mul_f32_e32 v177, 0xbfb8aa3b, v177
	v_mul_f32_e32 v181, 0xbfb8aa3b, v181
	v_mul_f32_e32 v182, 0xbfb8aa3b, v182
	v_mul_f32_e32 v161, 0xbfb8aa3b, v161
	v_exp_f32_e32 v177, v177
	v_exp_f32_e32 v181, v181
	v_exp_f32_e32 v182, v182
	v_exp_f32_e32 v161, v161
	v_add_f32_e32 v177, 1.0, v177
	v_add_f32_e32 v181, 1.0, v181
	v_add_f32_e32 v182, 1.0, v182
	v_add_f32_e32 v161, 1.0, v161
	v_rcp_f32_e32 v174, v174
	v_rcp_f32_e32 v175, v175
	v_rcp_f32_e32 v176, v176
	v_rcp_f32_e32 v177, v177
	v_rcp_f32_e32 v181, v181
	v_rcp_f32_e32 v182, v182
	v_rcp_f32_e32 v161, v161
	v_add_u32_e32 v190, 0xb0, v158
	v_cvt_pk_bf16_f32 v174, v174, v175
	v_cvt_pk_bf16_f32 v175, v177, v182
	v_cvt_pk_bf16_f32 v176, v180, v176
	v_cvt_pk_bf16_f32 v177, v181, v161
	global_store_dwordx4 v[178:179], v[174:177], off offset:256
	s_nop 1
	v_mov_b32_e32 v161, v247
	v_fma_f32 v140, v8, v161, v140
	v_mul_f32_e32 v140, 0xbfb8aa3b, v140
	v_fma_f32 v145, v13, v161, v145
	v_exp_f32_e32 v140, v140
	v_mul_f32_e32 v145, 0xbfb8aa3b, v145
	v_exp_f32_e32 v145, v145
	v_fma_f32 v141, v9, v161, v141
	v_add_f32_e32 v140, 1.0, v140
	v_mul_f32_e32 v141, 0xbfb8aa3b, v141
	v_rcp_f32_e32 v174, v140
	v_add_f32_e32 v140, 1.0, v145
	v_fma_f32 v145, v14, v161, v146
	v_exp_f32_e32 v141, v141
	v_mul_f32_e32 v145, 0xbfb8aa3b, v145
	v_exp_f32_e32 v145, v145
	v_fma_f32 v144, v12, v161, v144
	v_fma_f32 v142, v10, v161, v142
	v_mul_f32_e32 v144, 0xbfb8aa3b, v144
	v_add_f32_e32 v141, 1.0, v141
	v_mul_f32_e32 v142, 0xbfb8aa3b, v142
	v_fmac_f32_e32 v147, v15, v161
	v_fmac_f32_e32 v143, v11, v161
	v_exp_f32_e32 v144, v144
	v_exp_f32_e32 v142, v142
	v_rcp_f32_e32 v146, v141
	v_add_f32_e32 v141, 1.0, v145
	v_mul_f32_e32 v145, 0xbfb8aa3b, v147
	v_mul_f32_e32 v143, 0xbfb8aa3b, v143
	v_exp_f32_e32 v145, v145
	v_exp_f32_e32 v143, v143
	v_add_f32_e32 v144, 1.0, v144
	v_add_f32_e32 v142, 1.0, v142
	v_fma_f32 v132, v0, v161, v132
	v_rcp_f32_e32 v144, v144
	v_rcp_f32_e32 v140, v140
	v_rcp_f32_e32 v147, v142
	v_add_f32_e32 v142, 1.0, v145
	v_add_f32_e32 v143, 1.0, v143
	v_mul_f32_e32 v132, 0xbfb8aa3b, v132
	v_fma_f32 v137, v5, v161, v137
	v_rcp_f32_e32 v141, v141
	v_rcp_f32_e32 v142, v142
	v_rcp_f32_e32 v143, v143
	v_exp_f32_e32 v132, v132
	v_mul_f32_e32 v137, 0xbfb8aa3b, v137
	v_exp_f32_e32 v137, v137
	v_cvt_pk_bf16_f32 v140, v144, v140
	v_mad_i64_i32 v[144:145], s[0:1], v190, s31, v[166:167]
	v_cvt_pk_bf16_f32 v141, v141, v142
	v_cvt_pk_bf16_f32 v142, v174, v146
	v_cvt_pk_bf16_f32 v143, v147, v143
	v_lshl_add_u64 v[144:145], v[144:145], 0, v[168:169]
	v_add_f32_e32 v132, 1.0, v132
	v_fma_f32 v133, v1, v161, v133
	global_store_dwordx4 v[144:145], v[140:143], off
	v_mul_f32_e32 v133, 0xbfb8aa3b, v133
	v_exp_f32_e32 v133, v133
	v_rcp_f32_e32 v140, v132
	v_add_f32_e32 v132, 1.0, v137
	v_fma_f32 v137, v6, v161, v138
	v_mul_f32_e32 v137, 0xbfb8aa3b, v137
	v_exp_f32_e32 v137, v137
	v_fma_f32 v134, v2, v161, v134
	v_fma_f32 v136, v4, v161, v136
	v_add_f32_e32 v133, 1.0, v133
	v_mul_f32_e32 v134, 0xbfb8aa3b, v134
	v_fmac_f32_e32 v139, v7, v161
	v_fmac_f32_e32 v135, v3, v161
	v_mul_f32_e32 v136, 0xbfb8aa3b, v136
	v_exp_f32_e32 v134, v134
	v_rcp_f32_e32 v138, v133
	v_add_f32_e32 v133, 1.0, v137
	v_mul_f32_e32 v137, 0xbfb8aa3b, v139
	v_mul_f32_e32 v135, 0xbfb8aa3b, v135
	v_exp_f32_e32 v136, v136
	v_exp_f32_e32 v137, v137
	v_exp_f32_e32 v135, v135
	v_add_f32_e32 v134, 1.0, v134
	v_add_f32_e32 v136, 1.0, v136
	v_rcp_f32_e32 v139, v134
	v_add_f32_e32 v134, 1.0, v137
	v_add_f32_e32 v135, 1.0, v135
	v_rcp_f32_e32 v136, v136
	v_rcp_f32_e32 v132, v132
	v_rcp_f32_e32 v133, v133
	v_rcp_f32_e32 v134, v134
	v_rcp_f32_e32 v135, v135
	v_cvt_pk_bf16_f32 v132, v136, v132
	s_mov_b64 s[0:1], 0
	v_cvt_pk_bf16_f32 v133, v133, v134
	v_cvt_pk_bf16_f32 v134, v140, v138
	v_cvt_pk_bf16_f32 v135, v139, v135
	global_store_dwordx4 v[144:145], v[132:135], off offset:256

; __device__ __forceinline__ unsigned pk2(float lo, float hi) { return pg8::cvt_pk_bf16(lo, hi); }
;     __device__ __forceinline__ void operator()(const pg8::f32x4 (&acc)[2][2][4][2], const pg8::Unit& u, int wr, int wc, int fr, int fq) const {
;     ...
;         if (u.pn < 15) {
;             const float sc = ((u.pn % 6) < 2) ? QSCALE : 1.0f;
;             const int col0 = u.pn * 256 + wc * 32 + 8 * fq;
;             const bool vt_all = (u.pn == 4) | (u.pn == 5) | (u.pn == 10) | (u.pn == 11), vt_half = (u.pn == 14);
;             const int vrow0 = (u.pn <= 5 ? (u.pn - 4) * 256 : (u.pn <= 11 ? 512 + (u.pn - 10) * 256 : 1024 - 128)) + wc * 32 + 8 * fq;
; #pragma unroll
;             for (int ai = 0; ai < 2; ++ai)
; #pragma unroll
;                 for (int m = 0; m < 4; ++m) {
;                     const int row = row0 + ai * 128 + m * 16; const float rs = rstd_of(ssq, row) * sc;
; #pragma unroll
;                     for (int bj = 0; bj < 2; ++bj) {
;                         const pg8::f32x4 v0 = acc[ai][bj][m][0] * rs, v1 = acc[ai][bj][m][1] * rs;
;                         u32x4 w; w.x = pk2(v0[0], v0[1]); w.y = pk2(v0[2], v0[3]); w.z = pk2(v1[0], v1[1]); w.w = pk2(v1[2], v1[3]);
.LBB0_352:
	v_mov_b32_e32 v132, 0x3e38aa3b
	v_cndmask_b32_e64 v138, 1.0, v132, s[0:1]
	v_mov_b32_e32 v134, v236
	v_mul_f32_e32 v136, v138, v134
	v_or_b32_e32 v132, s19, v171
	s_movk_i32 s0, 0x1e00
	v_pk_mul_f32 v[130:131], v[130:131], v[136:137] op_sel_hi:[1,0]
	v_pk_mul_f32 v[128:129], v[128:129], v[136:137] op_sel_hi:[1,0]
	v_pk_mul_f32 v[140:141], v[126:127], v[136:137] op_sel_hi:[1,0]
	v_pk_mul_f32 v[126:127], v[124:125], v[136:137] op_sel_hi:[1,0]
	v_ashrrev_i32_e32 v133, 31, v132
	v_mad_i64_i32 v[134:135], s[0:1], v158, s0, 0
	v_cvt_pk_bf16_f32 v124, v128, v129
	v_cvt_pk_bf16_f32 v125, v130, v131
	v_cvt_pk_bf16_f32 v126, v126, v127
	s_andn2_b64 vcc, exec, s[42:43]
	v_cvt_pk_bf16_f32 v127, v140, v141
	s_cbranch_vccnz .LBB0_354
	v_lshl_add_u64 v[128:129], s[34:35], 0, v[134:135]
	v_lshl_add_u64 v[128:129], v[132:133], 1, v[128:129]
	global_store_dwordx4 v[128:129], v[124:127], off
	s_mov_b64 s[4:5], 0

; __device__ __forceinline__ unsigned pk2(float lo, float hi) { return pg8::cvt_pk_bf16(lo, hi); }
;     __device__ __forceinline__ void operator()(const pg8::f32x4 (&acc)[2][2][4][2], const pg8::Unit& u, int wr, int wc, int fr, int fq) const {
;     ...
;                 for (int m = 0; m < 4; ++m) {
;                     const int row = row0 + ai * 128 + m * 16; const float rs = rstd_of(ssq, row) * sc;
; #pragma unroll
;                     for (int bj = 0; bj < 2; ++bj) {
;                         const pg8::f32x4 v0 = acc[ai][bj][m][0] * rs, v1 = acc[ai][bj][m][1] * rs;
;                         u32x4 w; w.x = pk2(v0[0], v0[1]); w.y = pk2(v0[2], v0[3]); w.z = pk2(v1[0], v1[1]); w.w = pk2(v1[2], v1[3]);
.LBB0_369:
	v_mov_b32_e32 v116, v237
	v_mul_f32_e32 v118, v138, v116
	s_movk_i32 s19, 0x1e00
	v_pk_mul_f32 v[114:115], v[114:115], v[118:119] op_sel_hi:[1,0]
	v_pk_mul_f32 v[112:113], v[112:113], v[118:119] op_sel_hi:[1,0]
	v_pk_mul_f32 v[120:121], v[110:111], v[118:119] op_sel_hi:[1,0]
	v_pk_mul_f32 v[110:111], v[108:109], v[118:119] op_sel_hi:[1,0]
	v_mad_i64_i32 v[116:117], s[46:47], v164, s19, 0
	v_cvt_pk_bf16_f32 v108, v112, v113
	v_cvt_pk_bf16_f32 v109, v114, v115
	v_cvt_pk_bf16_f32 v110, v110, v111
	s_andn2_b64 vcc, exec, s[44:45]
	v_cvt_pk_bf16_f32 v111, v120, v121
	s_cbranch_vccz .LBB0_373
	s_andn2_b64 vcc, exec, s[0:1]
	s_cbranch_vccz .LBB0_374

; __device__ __forceinline__ unsigned pk2(float lo, float hi) { return pg8::cvt_pk_bf16(lo, hi); }
;     __device__ __forceinline__ void operator()(const pg8::f32x4 (&acc)[2][2][4][2], const pg8::Unit& u, int wr, int wc, int fr, int fq) const {
;     ...
;                 for (int m = 0; m < 4; ++m) {
;                     const int row = row0 + ai * 128 + m * 16; const float rs = rstd_of(ssq, row) * sc;
; #pragma unroll
;                     for (int bj = 0; bj < 2; ++bj) {
;                         const pg8::f32x4 v0 = acc[ai][bj][m][0] * rs, v1 = acc[ai][bj][m][1] * rs;
;                         u32x4 w; w.x = pk2(v0[0], v0[1]); w.y = pk2(v0[2], v0[3]); w.z = pk2(v1[0], v1[1]); w.w = pk2(v1[2], v1[3]);
.LBB0_386:
	v_mov_b32_e32 v100, v238
	v_mul_f32_e32 v102, v138, v100
	s_movk_i32 s19, 0x1e00
	v_pk_mul_f32 v[98:99], v[98:99], v[102:103] op_sel_hi:[1,0]
	v_pk_mul_f32 v[96:97], v[96:97], v[102:103] op_sel_hi:[1,0]
	v_pk_mul_f32 v[104:105], v[94:95], v[102:103] op_sel_hi:[1,0]
	v_pk_mul_f32 v[94:95], v[92:93], v[102:103] op_sel_hi:[1,0]
	v_mad_i64_i32 v[100:101], s[46:47], v162, s19, 0
	v_cvt_pk_bf16_f32 v92, v96, v97
	v_cvt_pk_bf16_f32 v93, v98, v99
	v_cvt_pk_bf16_f32 v94, v94, v95
	s_andn2_b64 vcc, exec, s[44:45]
	v_cvt_pk_bf16_f32 v95, v104, v105
	s_cbranch_vccz .LBB0_390
	s_andn2_b64 vcc, exec, s[0:1]
	s_cbranch_vccz .LBB0_391

; __device__ __forceinline__ unsigned pk2(float lo, float hi) { return pg8::cvt_pk_bf16(lo, hi); }
;     __device__ __forceinline__ void operator()(const pg8::f32x4 (&acc)[2][2][4][2], const pg8::Unit& u, int wr, int wc, int fr, int fq) const {
;     ...
;                 for (int m = 0; m < 4; ++m) {
;                     const int row = row0 + ai * 128 + m * 16; const float rs = rstd_of(ssq, row) * sc;
; #pragma unroll
;                     for (int bj = 0; bj < 2; ++bj) {
;                         const pg8::f32x4 v0 = acc[ai][bj][m][0] * rs, v1 = acc[ai][bj][m][1] * rs;
;                         u32x4 w; w.x = pk2(v0[0], v0[1]); w.y = pk2(v0[2], v0[3]); w.z = pk2(v1[0], v1[1]); w.w = pk2(v1[2], v1[3]);
.LBB0_403:
	v_mov_b32_e32 v84, v239
	v_mul_f32_e32 v86, v138, v84
	s_movk_i32 s19, 0x1e00
	v_pk_mul_f32 v[82:83], v[82:83], v[86:87] op_sel_hi:[1,0]
	v_pk_mul_f32 v[80:81], v[80:81], v[86:87] op_sel_hi:[1,0]
	v_pk_mul_f32 v[88:89], v[78:79], v[86:87] op_sel_hi:[1,0]
	v_pk_mul_f32 v[78:79], v[76:77], v[86:87] op_sel_hi:[1,0]
	v_mad_i64_i32 v[84:85], s[46:47], v160, s19, 0
	v_cvt_pk_bf16_f32 v76, v80, v81
	v_cvt_pk_bf16_f32 v77, v82, v83
	v_cvt_pk_bf16_f32 v78, v78, v79
	s_andn2_b64 vcc, exec, s[44:45]
	v_cvt_pk_bf16_f32 v79, v88, v89
	s_cbranch_vccz .LBB0_407
	s_andn2_b64 vcc, exec, s[0:1]
	s_cbranch_vccz .LBB0_408

; __device__ __forceinline__ unsigned pk2(float lo, float hi) { return pg8::cvt_pk_bf16(lo, hi); }
;     __device__ __forceinline__ void operator()(const pg8::f32x4 (&acc)[2][2][4][2], const pg8::Unit& u, int wr, int wc, int fr, int fq) const {
;     ...
;                 for (int m = 0; m < 4; ++m) {
;                     const int row = row0 + ai * 128 + m * 16; const float rs = rstd_of(ssq, row) * sc;
; #pragma unroll
;                     for (int bj = 0; bj < 2; ++bj) {
;                         const pg8::f32x4 v0 = acc[ai][bj][m][0] * rs, v1 = acc[ai][bj][m][1] * rs;
;                         u32x4 w; w.x = pk2(v0[0], v0[1]); w.y = pk2(v0[2], v0[3]); w.z = pk2(v1[0], v1[1]); w.w = pk2(v1[2], v1[3]);
.LBB0_420:
	v_mov_b32_e32 v69, v244
	v_mul_f32_e32 v70, v138, v69
	s_movk_i32 s19, 0x1e00
	v_pk_mul_f32 v[66:67], v[66:67], v[70:71] op_sel_hi:[1,0]
	v_pk_mul_f32 v[64:65], v[64:65], v[70:71] op_sel_hi:[1,0]
	v_pk_mul_f32 v[72:73], v[62:63], v[70:71] op_sel_hi:[1,0]
	v_pk_mul_f32 v[62:63], v[60:61], v[70:71] op_sel_hi:[1,0]
	v_mad_i64_i32 v[68:69], s[46:47], v68, s19, 0
	v_cvt_pk_bf16_f32 v60, v64, v65
	v_cvt_pk_bf16_f32 v61, v66, v67
	v_cvt_pk_bf16_f32 v62, v62, v63
	s_andn2_b64 vcc, exec, s[44:45]
	v_cvt_pk_bf16_f32 v63, v72, v73
	s_cbranch_vccz .LBB0_424
	s_andn2_b64 vcc, exec, s[0:1]
	s_cbranch_vccz .LBB0_425

; __device__ __forceinline__ unsigned pk2(float lo, float hi) { return pg8::cvt_pk_bf16(lo, hi); }
;     __device__ __forceinline__ void operator()(const pg8::f32x4 (&acc)[2][2][4][2], const pg8::Unit& u, int wr, int wc, int fr, int fq) const {
;     ...
;                 for (int m = 0; m < 4; ++m) {
;                     const int row = row0 + ai * 128 + m * 16; const float rs = rstd_of(ssq, row) * sc;
; #pragma unroll
;                     for (int bj = 0; bj < 2; ++bj) {
;                         const pg8::f32x4 v0 = acc[ai][bj][m][0] * rs, v1 = acc[ai][bj][m][1] * rs;
;                         u32x4 w; w.x = pk2(v0[0], v0[1]); w.y = pk2(v0[2], v0[3]); w.z = pk2(v1[0], v1[1]); w.w = pk2(v1[2], v1[3]);
.LBB0_437:
	v_mov_b32_e32 v53, v245
	v_mul_f32_e32 v54, v138, v53
	s_movk_i32 s19, 0x1e00
	v_pk_mul_f32 v[50:51], v[50:51], v[54:55] op_sel_hi:[1,0]
	v_pk_mul_f32 v[48:49], v[48:49], v[54:55] op_sel_hi:[1,0]
	v_pk_mul_f32 v[56:57], v[46:47], v[54:55] op_sel_hi:[1,0]
	v_pk_mul_f32 v[46:47], v[44:45], v[54:55] op_sel_hi:[1,0]
	v_mad_i64_i32 v[52:53], s[46:47], v52, s19, 0
	v_cvt_pk_bf16_f32 v44, v48, v49
	v_cvt_pk_bf16_f32 v45, v50, v51
	v_cvt_pk_bf16_f32 v46, v46, v47
	s_andn2_b64 vcc, exec, s[44:45]
	v_cvt_pk_bf16_f32 v47, v56, v57
	s_cbranch_vccz .LBB0_441
	s_andn2_b64 vcc, exec, s[0:1]
	s_cbranch_vccz .LBB0_442

; __device__ __forceinline__ unsigned pk2(float lo, float hi) { return pg8::cvt_pk_bf16(lo, hi); }
;     __device__ __forceinline__ void operator()(const pg8::f32x4 (&acc)[2][2][4][2], const pg8::Unit& u, int wr, int wc, int fr, int fq) const {
;     ...
;                 for (int m = 0; m < 4; ++m) {
;                     const int row = row0 + ai * 128 + m * 16; const float rs = rstd_of(ssq, row) * sc;
; #pragma unroll
;                     for (int bj = 0; bj < 2; ++bj) {
;                         const pg8::f32x4 v0 = acc[ai][bj][m][0] * rs, v1 = acc[ai][bj][m][1] * rs;
;                         u32x4 w; w.x = pk2(v0[0], v0[1]); w.y = pk2(v0[2], v0[3]); w.z = pk2(v1[0], v1[1]); w.w = pk2(v1[2], v1[3]);
.LBB0_454:
	v_mov_b32_e32 v37, v246
	v_mul_f32_e32 v38, v138, v37
	s_movk_i32 s19, 0x1e00
	v_pk_mul_f32 v[30:31], v[30:31], v[38:39] op_sel_hi:[1,0]
	v_pk_mul_f32 v[28:29], v[28:29], v[38:39] op_sel_hi:[1,0]
	v_pk_mul_f32 v[40:41], v[26:27], v[38:39] op_sel_hi:[1,0]
	v_pk_mul_f32 v[26:27], v[24:25], v[38:39] op_sel_hi:[1,0]
	v_mad_i64_i32 v[36:37], s[46:47], v36, s19, 0
	v_cvt_pk_bf16_f32 v24, v28, v29
	v_cvt_pk_bf16_f32 v25, v30, v31
	v_cvt_pk_bf16_f32 v26, v26, v27
	s_andn2_b64 vcc, exec, s[44:45]
	v_cvt_pk_bf16_f32 v27, v40, v41
	s_cbranch_vccz .LBB0_458
	s_andn2_b64 vcc, exec, s[0:1]
	s_cbranch_vccz .LBB0_459

; __device__ __forceinline__ unsigned pk2(float lo, float hi) { return pg8::cvt_pk_bf16(lo, hi); }
;     __device__ __forceinline__ void operator()(const pg8::f32x4 (&acc)[2][2][4][2], const pg8::Unit& u, int wr, int wc, int fr, int fq) const {
;     ...
;                 for (int m = 0; m < 4; ++m) {
;                     const int row = row0 + ai * 128 + m * 16; const float rs = rstd_of(ssq, row) * sc;
; #pragma unroll
;                     for (int bj = 0; bj < 2; ++bj) {
;                         const pg8::f32x4 v0 = acc[ai][bj][m][0] * rs, v1 = acc[ai][bj][m][1] * rs;
;                         u32x4 w; w.x = pk2(v0[0], v0[1]); w.y = pk2(v0[2], v0[3]); w.z = pk2(v1[0], v1[1]); w.w = pk2(v1[2], v1[3]);
.LBB0_471:
	v_mov_b32_e32 v17, v247
	v_mul_f32_e32 v18, v138, v17
	s_movk_i32 s19, 0x1e00
	v_pk_mul_f32 v[14:15], v[14:15], v[18:19] op_sel_hi:[1,0]
	v_pk_mul_f32 v[12:13], v[12:13], v[18:19] op_sel_hi:[1,0]
	v_pk_mul_f32 v[20:21], v[10:11], v[18:19] op_sel_hi:[1,0]
	v_pk_mul_f32 v[10:11], v[8:9], v[18:19] op_sel_hi:[1,0]
	v_mad_i64_i32 v[16:17], s[46:47], v16, s19, 0
	v_cvt_pk_bf16_f32 v8, v12, v13
	v_cvt_pk_bf16_f32 v9, v14, v15
	v_cvt_pk_bf16_f32 v10, v10, v11
	s_andn2_b64 vcc, exec, s[44:45]
	v_cvt_pk_bf16_f32 v11, v20, v21
	s_cbranch_vccz .LBB0_475
	s_andn2_b64 vcc, exec, s[0:1]
	s_cbranch_vccz .LBB0_476

; #define PG8_STAGE(bufoff, gbase, voff) do { _Pragma("unroll") for (int _i = 0; _i < 2; ++_i) \
;         __builtin_amdgcn_global_load_lds((const unsigned*)((const char*)(gbase) + (voff)[_i]), (PG8_LAS unsigned*)(lds + (bufoff) + ldsw + _i * 8192), 16, 0, 0); } while (0)
; #define PG8_WAIT_V(n) asm volatile("s_waitcnt vmcnt(" #n ")" ::: "memory")
; #define PG8_BAR __builtin_amdgcn_s_barrier()
; template <class Epi, class Sched, bool ALIGN_EPI = false, bool SP2 = false>
; __device__ __forceinline__ void gemm_phase(PG8_LAS unsigned char* lds, const Gemm g, const Sched& S, const Epi& E) {
;     ...
;     for (int i = 0; i < 2; ++i) { int R, C; stage_rc(tid * 16 + i * 8192, R, C); const int Rb = Epi::PERM ? ((R & ~31) + perm32(R & 31)) : R;
;         voffA[i] = (unsigned)(R * K + C) * 2u; voffB[i] = (unsigned)(Rb * K + C) * 2u; }
;     const size_t kstep = (size_t)(BK * 2);
;     const size_t hstep = (size_t)HALF * K * 2;
;     const size_t tstep = 2 * hstep;
;     const unsigned ldsw = (unsigned)wid * 1024u;
;     const int aoff = lds_byte(wr * 64 + fr, fq * 8), boff = lds_byte(wc * 32 + fr, fq * 8);
;     ...
;     const char* cA = (const char*)g.A + (size_t)cur.pm * tstep; const char* cB = (const char*)g.Bt + (size_t)cur.pn * tstep;
;     S.a_ready(cur);
;     if constexpr (SP2) {
;         PG8_STAGE(PG8_SB(0, 0), cB, voffB); PG8_STAGE(PG8_SB(0, 1), cB + hstep, voffB); PG8_STAGE(PG8_SA(0, 0), cA, voffA); PG8_STAGE(PG8_SA(0, 1), cA + hstep, voffA);
;         if (wr == 1) PG8_BAR;
;         PG8_WAIT_V(2); PG8_BAR;
;         PG8_STAGE(PG8_SB(1, 0), cB + kstep, voffB); PG8_STAGE(PG8_SA(1, 0), cA + kstep, voffA); PG8_STAGE(PG8_SB(1, 1), cB + hstep + kstep, voffB);
;         PG8_WAIT_V(6); PG8_BAR;
.LBB0_617:
	v_readlane_b32 s10, v255, 9
	v_readlane_b32 s11, v255, 10
	s_mul_i32 s13, s10, 3
	v_readlane_b32 s10, v255, 16
	v_readlane_b32 s11, v255, 17
	s_and_b64 s[10:11], s[10:11], exec
	s_cselect_b32 s10, 2, 0
	s_add_i32 s10, s10, s13
	s_ashr_i32 s11, s10, 31
	s_lshl_b64 s[10:11], s[10:11], 20
	v_readlane_b32 s14, v252, 8
	v_lshrrev_b32_e32 v16, 1, v10
	v_readlane_b32 s15, v252, 9
	s_add_u32 s10, s14, s10
	v_and_b32_e32 v16, 24, v16
	v_readlane_b32 s18, v253, 59
	s_addc_u32 s11, s15, s11
	v_and_b32_e32 v11, 15, v10
	v_lshlrev_b32_e32 v17, 1, v16
	v_lshlrev_b32_e32 v10, 2, v10
	s_lshl_b32 s1, s1, 5
	v_mov_b32_e32 v135, v197
	v_readlane_b32 s19, v253, 60
	v_lshl_or_b32 v35, s12, 6, v11
	v_lshl_or_b32 v11, v11, 6, v17
	s_lshl_b32 s12, s12, 13
	v_and_b32_e32 v10, 32, v10
	s_and_b32 s1, s1, 0x60
	s_add_i32 m0, s44, 0x18000
	v_lshl_add_u64 v[0:1], v[0:1], 0, s[36:37]
	v_lshl_add_u64 v[12:13], s[18:19], 0, v[134:135]
	v_mov_b32_e32 v133, v197
	v_bitop3_b32 v17, v11, s12, v10 bitop3:0xde
	s_lshl_b32 s12, s1, 7
	s_waitcnt vmcnt(2)
	s_barrier
	global_load_lds_dwordx4 v[0:1], off
	v_lshl_add_u64 v[0:1], v[2:3], 0, s[36:37]
	s_add_i32 m0, s44, 0x1a000
	s_add_i32 s49, s44, 0x8000
	s_add_i32 s50, s44, 0xa000
	v_lshl_add_u64 v[14:15], s[18:19], 0, v[132:133]
	s_waitcnt vmcnt(0)
	v_bitop3_b32 v147, v11, s12, v10 bitop3:0xde
	global_load_lds_dwordx4 v[0:1], off
	v_lshl_add_u64 v[0:1], v[12:13], 0, s[36:37]
	s_mov_b32 m0, s49
	s_add_u32 s12, s22, 0x40080
	global_load_lds_dwordx4 v[0:1], off
	v_lshl_add_u64 v[0:1], v[14:15], 0, s[36:37]
	s_mov_b32 m0, s50
	s_addc_u32 s13, s23, 0
	global_load_lds_dwordx4 v[0:1], off
	s_add_i32 m0, s44, 0x1c000
	v_lshl_add_u64 v[0:1], s[12:13], 0, v[196:197]
	global_load_lds_dwordx4 v[0:1], off
	v_lshl_add_u64 v[0:1], s[12:13], 0, v[32:33]
	s_add_i32 m0, s44, 0x1e000
	s_cmpk_lt_u32 s0, 0x100
	global_load_lds_dwordx4 v[0:1], off
	v_lshlrev_b32_e32 v0, 14, v8
	v_and_b32_e32 v0, 0xffff8000, v0
	v_lshl_add_u32 v0, v7, 11, v0
	v_and_b32_e32 v1, 1, v8
	v_lshl_or_b32 v0, v1, 6, v0
	v_lshl_add_u32 v136, v9, 1, v0
	v_lshlrev_b32_e32 v0, 14, v4
	v_and_b32_e32 v0, 0xffff8000, v0
	s_waitcnt vmcnt(6)
	v_or_b32_e32 v148, s1, v16
	v_lshl_add_u32 v0, v5, 11, v0
	v_and_b32_e32 v1, 1, v4
	v_readlane_b32 s0, v253, 57
	v_lshl_or_b32 v0, v1, 6, v0
	v_readlane_b32 s1, v253, 58
	s_mov_b32 s48, 0
	s_cselect_b64 s[12:13], -1, 0
	v_mov_b32_e32 v137, v197
	v_lshl_add_u32 v138, v6, 1, v0
	v_mov_b32_e32 v139, v197
	v_add_u32_e32 v149, 0, v17
	v_readlane_b32 s51, v253, 52
	s_mov_b32 s52, s0
	s_mov_b64 s[0:1], s[18:19]
	s_barrier
	v_mov_b32_e32 v240, -1
	s_branch .LBB0_620

; __device__ __forceinline__ float rstd_of(const float* ssq, int row) {
;     const f32x4* q = (const f32x4*)(ssq + (size_t)row * 16); const f32x4 a = q[0], b = q[1], c = q[2], d = q[3];
;     const float t = (((a.x + a.y) + (a.z + a.w)) + ((b.x + b.y) + (b.z + b.w))) + (((c.x + c.y) + (c.z + c.w)) + ((d.x + d.y) + (d.z + d.w)));
;     return 1.0f / sqrtf(t * (1.0f / DM) + 1e-6f); }
;     __device__ __forceinline__ void operator()(const pg8::f32x4 (&acc)[2][2][4][2], const pg8::Unit& u, int wr, int wc, int fr, int fq) const {
;     ...
;             for (int m = 0; m < 4; ++m) {
;                 const int row = row0 + ai * 128 + m * 16; const float rs = rstd_of(ssq, row);
.LBB0_626:
	v_lshl_add_u32 v142, s52, 8, v35
	v_readfirstlane_b32 s100, v240
	s_cmp_eq_u32 s100, s52
	s_cbranch_scc1 .Lrstd_have_sw
	v_mbcnt_lo_u32_b32 v206, -1, 0
	v_mbcnt_hi_u32_b32 v206, -1, v206
	v_lshrrev_b32_e32 v207, 4, v206
	v_and_b32_e32 v208, 1, v207
	v_lshrrev_b32_e32 v207, 1, v207
	v_lshlrev_b32_e32 v208, 5, v208
	v_lshl_add_u32 v208, v207, 7, v208
	v_add_u32_e32 v208, v208, v142
	v_mov_b32_e32 v209, 0
	v_lshlrev_b64 v[208:209], 6, v[208:209]
	v_lshl_add_u64 v[208:209], s[10:11], 0, v[208:209]
	global_load_dwordx4 v[166:169], v[208:209], off
	global_load_dwordx4 v[170:173], v[208:209], off offset:16
	global_load_dwordx4 v[174:177], v[208:209], off offset:32
	global_load_dwordx4 v[178:181], v[208:209], off offset:48
	global_load_dwordx4 v[182:185], v[208:209], off offset:1024
	global_load_dwordx4 v[186:189], v[208:209], off offset:1040
	global_load_dwordx4 v[190:193], v[208:209], off offset:1056
	global_load_dwordx4 v[202:205], v[208:209], off offset:1072
	v_and_b32_e32 v210, 15, v206
	v_lshlrev_b32_e32 v210, 2, v210
	v_add_u32_e32 v211, 64, v210
	v_add_u32_e32 v212, 0x80, v210
	v_add_u32_e32 v213, 0xc0, v210
	s_waitcnt vmcnt(4)
	v_add_f32_e32 v166, v166, v167
	v_add_f32_e32 v168, v168, v169
	v_add_f32_e32 v166, v166, v168
	v_add_f32_e32 v170, v170, v171
	v_add_f32_e32 v172, v172, v173
	v_add_f32_e32 v170, v170, v172
	v_add_f32_e32 v174, v174, v175
	v_add_f32_e32 v176, v176, v177
	v_add_f32_e32 v174, v174, v176
	v_add_f32_e32 v178, v178, v179
	v_add_f32_e32 v180, v180, v181
	v_add_f32_e32 v178, v178, v180
	v_add_f32_e32 v166, v166, v170
	v_add_f32_e32 v174, v174, v178
	v_add_f32_e32 v166, v166, v174
	v_fmamk_f32 v166, v166, 0x3a800000, v229
	v_cmp_gt_f32_e32 vcc, 0xf800000, v166
	v_mul_f32_e32 v171, 0x4f800000, v166
	s_nop 0
	v_cndmask_b32_e32 v166, v166, v171, vcc
	v_sqrt_f32_e32 v171, v166
	s_nop 0
	v_add_u32_e32 v172, -1, v171
	v_fma_f32 v173, -v172, v171, v166
	v_cmp_ge_f32_e64 s[100:101], 0, v173
	v_add_u32_e32 v173, 1, v171
	s_nop 0
	v_cndmask_b32_e64 v172, v171, v172, s[100:101]
	v_fma_f32 v171, -v173, v171, v166
	v_cmp_lt_f32_e64 s[100:101], 0, v171
	s_nop 1
	v_cndmask_b32_e64 v171, v172, v173, s[100:101]
	v_mul_f32_e32 v172, 0x37800000, v171
	v_cndmask_b32_e32 v171, v171, v172, vcc
	v_cmp_class_f32_e32 vcc, v166, v230
	s_nop 1
	v_cndmask_b32_e32 v166, v171, v166, vcc
	v_div_scale_f32 v171, s[100:101], v166, v166, 1.0
	v_rcp_f32_e32 v172, v171
	s_nop 0
	v_fma_f32 v173, -v171, v172, 1.0
	v_fmac_f32_e32 v172, v173, v172
	v_div_scale_f32 v173, vcc, 1.0, v166, 1.0
	v_mul_f32_e32 v175, v173, v172
	v_fma_f32 v176, -v171, v175, v173
	v_fmac_f32_e32 v175, v176, v172
	v_fma_f32 v171, -v171, v175, v173
	v_div_fmas_f32 v171, v171, v172, v175
	v_div_fixup_f32 v214, v171, v166, 1.0
	s_waitcnt vmcnt(0)
	v_add_f32_e32 v182, v182, v183
	v_add_f32_e32 v184, v184, v185
	v_add_f32_e32 v182, v182, v184
	v_add_f32_e32 v186, v186, v187
	v_add_f32_e32 v188, v188, v189
	v_add_f32_e32 v186, v186, v188
	v_add_f32_e32 v190, v190, v191
	v_add_f32_e32 v192, v192, v193
	v_add_f32_e32 v190, v190, v192
	v_add_f32_e32 v202, v202, v203
	v_add_f32_e32 v204, v204, v205
	v_add_f32_e32 v202, v202, v204
	v_add_f32_e32 v182, v182, v186
	v_add_f32_e32 v190, v190, v202
	v_add_f32_e32 v182, v182, v190
	v_fmamk_f32 v182, v182, 0x3a800000, v229
	v_cmp_gt_f32_e32 vcc, 0xf800000, v182
	v_mul_f32_e32 v187, 0x4f800000, v182
	s_nop 0
	v_cndmask_b32_e32 v182, v182, v187, vcc
	v_sqrt_f32_e32 v187, v182
	s_nop 0
	v_add_u32_e32 v188, -1, v187
	v_fma_f32 v189, -v188, v187, v182
	v_cmp_ge_f32_e64 s[100:101], 0, v189
	v_add_u32_e32 v189, 1, v187
	s_nop 0
	v_cndmask_b32_e64 v188, v187, v188, s[100:101]
	v_fma_f32 v187, -v189, v187, v182
	v_cmp_lt_f32_e64 s[100:101], 0, v187
	s_nop 1
	v_cndmask_b32_e64 v187, v188, v189, s[100:101]
	v_mul_f32_e32 v188, 0x37800000, v187
	v_cndmask_b32_e32 v187, v187, v188, vcc
	v_cmp_class_f32_e32 vcc, v182, v230
	s_nop 1
	v_cndmask_b32_e32 v182, v187, v182, vcc
	v_div_scale_f32 v187, s[100:101], v182, v182, 1.0
	v_rcp_f32_e32 v188, v187
	s_nop 0
	v_fma_f32 v189, -v187, v188, 1.0
	v_fmac_f32_e32 v188, v189, v188
	v_div_scale_f32 v189, vcc, 1.0, v182, 1.0
	v_mul_f32_e32 v191, v189, v188
	v_fma_f32 v192, -v187, v191, v189
	v_fmac_f32_e32 v191, v192, v188
	v_fma_f32 v187, -v187, v191, v189
	v_div_fmas_f32 v187, v187, v188, v191
	v_div_fixup_f32 v215, v187, v182, 1.0
	ds_bpermute_b32 v236, v210, v214
	ds_bpermute_b32 v237, v210, v215
	ds_bpermute_b32 v238, v211, v214
	ds_bpermute_b32 v239, v211, v215
	ds_bpermute_b32 v244, v212, v214
	ds_bpermute_b32 v245, v212, v215
	ds_bpermute_b32 v246, v213, v214
	ds_bpermute_b32 v247, v213, v215
	s_waitcnt lgkmcnt(0)
	v_mov_b32_e32 v240, s52
; __device__ __forceinline__ unsigned pk2(float lo, float hi) { return pg8::cvt_pk_bf16(lo, hi); }
; __device__ __forceinline__ float fast_exp2(float x) { return __builtin_amdgcn_exp2f(x); }
; __device__ __forceinline__ float fast_rcp(float x) { return __builtin_amdgcn_rcpf(x); }
;     __device__ __forceinline__ void operator()(const pg8::f32x4 (&acc)[2][2][4][2], const pg8::Unit& u, int wr, int wc, int fr, int fq) const {
;         const int row0 = u.pm * 256 + wr * 64 + fr, col0 = u.pn * 128 + wc * 32 + 8 * fq;
; #pragma unroll
;         for (int ai = 0; ai < 2; ++ai)
; #pragma unroll
;             for (int m = 0; m < 4; ++m) {
;                 const int row = row0 + ai * 128 + m * 16; const float rs = rstd_of(ssq, row);
;                 bf16_t* dst = O + (size_t)row * DFF + col0;
;                 float v[8];
; #pragma unroll
;                 for (int n = 0; n < 2; ++n)
; #pragma unroll
;                     for (int j = 0; j < 4; ++j) { const float g = acc[ai][0][m][n][j] * rs, uu = acc[ai][1][m][n][j] * rs; v[n * 4 + j] = g * fast_rcp(1.0f + fast_exp2(-g * LOG2E)) * uu; }
;                 u32x4 w; w.x = pk2(v[0], v[1]); w.y = pk2(v[2], v[3]); w.z = pk2(v[4], v[5]); w.w = pk2(v[6], v[7]);
;                 *(u32x4*)dst = w;
;             }
.Lrstd_have_sw:
	s_mov_b32 s15, 0xf800000
	v_lshl_or_b32 v144, s51, 7, v148
	v_ashrrev_i32_e32 v145, 31, v144
	s_movk_i32 s17, 0x1600
	s_nop 1
	v_readlane_b32 s0, v252, 4
	v_readlane_b32 s1, v252, 5
	v_mov_b32_e32 v146, v236
	v_pk_mul_f32 v[128:129], v[128:129], v[146:147] op_sel_hi:[1,0]
	v_pk_mul_f32 v[120:121], v[120:121], v[146:147] op_sel_hi:[1,0]
	v_mul_f32_e32 v143, 0xbfb8aa3b, v128
	v_exp_f32_e32 v143, v143
	v_pk_mul_f32 v[122:123], v[122:123], v[146:147] op_sel_hi:[1,0]
	v_pk_mul_f32 v[124:125], v[124:125], v[146:147] op_sel_hi:[1,0]
	v_pk_mul_f32 v[116:117], v[116:117], v[146:147] op_sel_hi:[1,0]
	v_add_f32_e32 v143, 1.0, v143
	v_rcp_f32_e32 v152, v143
	v_mul_f32_e32 v143, 0xbfb8aa3b, v129
	v_exp_f32_e32 v143, v143
	v_pk_mul_f32 v[118:119], v[118:119], v[146:147] op_sel_hi:[1,0]
	v_mov_b64_e32 v[140:141], s[0:1]
	v_mad_i64_i32 v[150:151], s[0:1], v142, s17, v[140:141]
	v_add_f32_e32 v143, 1.0, v143
	v_rcp_f32_e32 v153, v143
	s_nop 0
	v_pk_mul_f32 v[128:129], v[128:129], v[152:153]
	s_nop 0
	v_pk_mul_f32 v[120:121], v[120:121], v[128:129]
	v_pk_mul_f32 v[128:129], v[130:131], v[146:147] op_sel_hi:[1,0]
	s_nop 0
	v_mul_f32_e32 v130, 0xbfb8aa3b, v128
	v_mul_f32_e32 v131, 0xbfb8aa3b, v129
	v_exp_f32_e32 v130, v130
	v_exp_f32_e32 v131, v131
	v_add_f32_e32 v130, 1.0, v130
	v_add_f32_e32 v131, 1.0, v131
	v_rcp_f32_e32 v130, v130
	v_rcp_f32_e32 v131, v131
	s_nop 0
	v_pk_mul_f32 v[128:129], v[128:129], v[130:131]
	s_nop 0
	v_pk_mul_f32 v[122:123], v[122:123], v[128:129]
	v_mul_f32_e32 v128, 0xbfb8aa3b, v124
	v_mul_f32_e32 v129, 0xbfb8aa3b, v125
	v_exp_f32_e32 v128, v128
	v_exp_f32_e32 v129, v129
	v_add_f32_e32 v128, 1.0, v128
	v_add_f32_e32 v129, 1.0, v129
	v_rcp_f32_e32 v128, v128
	v_rcp_f32_e32 v129, v129
	s_nop 0
	v_pk_mul_f32 v[124:125], v[124:125], v[128:129]
	s_nop 0
	v_pk_mul_f32 v[128:129], v[116:117], v[124:125]
	v_pk_mul_f32 v[116:117], v[126:127], v[146:147] op_sel_hi:[1,0]
	s_nop 0
	v_mul_f32_e32 v124, 0xbfb8aa3b, v116
	v_mul_f32_e32 v125, 0xbfb8aa3b, v117
	v_exp_f32_e32 v124, v124
	v_exp_f32_e32 v125, v125
	v_add_f32_e32 v124, 1.0, v124
	v_add_f32_e32 v125, 1.0, v125
	v_rcp_f32_e32 v124, v124
	v_rcp_f32_e32 v125, v125
	s_nop 0
	v_pk_mul_f32 v[116:117], v[116:117], v[124:125]
	s_nop 0
	v_pk_mul_f32 v[126:127], v[118:119], v[116:117]
	v_lshlrev_b64 v[124:125], 1, v[144:145]
	v_cvt_pk_bf16_f32 v119, v126, v127
	v_or_b32_e32 v126, 16, v142
	v_lshl_add_u64 v[130:131], v[150:151], 0, v[124:125]
	v_cvt_pk_bf16_f32 v116, v120, v121
	v_cvt_pk_bf16_f32 v117, v122, v123
	v_cvt_pk_bf16_f32 v118, v128, v129
	global_store_dwordx4 v[130:131], v[116:119], off
	s_nop 1
	v_mov_b32_e32 v116, v237
	v_pk_mul_f32 v[112:113], v[112:113], v[116:117] op_sel_hi:[1,0]
	v_mad_i64_i32 v[118:119], s[0:1], v126, s17, v[140:141]
	v_mul_f32_e32 v117, 0xbfb8aa3b, v112
	v_exp_f32_e32 v117, v117
	s_nop 0
	v_add_f32_e32 v117, 1.0, v117
	v_rcp_f32_e32 v120, v117
	v_pk_mul_f32 v[104:105], v[104:105], v[116:117] op_sel_hi:[1,0]
	v_mul_f32_e32 v117, 0xbfb8aa3b, v113
	v_exp_f32_e32 v117, v117
	s_nop 0
	v_add_f32_e32 v117, 1.0, v117
	v_rcp_f32_e32 v121, v117
	v_pk_mul_f32 v[106:107], v[106:107], v[116:117] op_sel_hi:[1,0]
	v_pk_mul_f32 v[108:109], v[108:109], v[116:117] op_sel_hi:[1,0]
	v_pk_mul_f32 v[100:101], v[100:101], v[116:117] op_sel_hi:[1,0]
	v_pk_mul_f32 v[112:113], v[112:113], v[120:121]
	v_pk_mul_f32 v[102:103], v[102:103], v[116:117] op_sel_hi:[1,0]
	v_pk_mul_f32 v[104:105], v[104:105], v[112:113]
	v_pk_mul_f32 v[112:113], v[114:115], v[116:117] op_sel_hi:[1,0]
	s_nop 0
	v_mul_f32_e32 v114, 0xbfb8aa3b, v112
	v_mul_f32_e32 v115, 0xbfb8aa3b, v113
	v_exp_f32_e32 v114, v114
	v_exp_f32_e32 v115, v115
	v_add_f32_e32 v114, 1.0, v114
	v_add_f32_e32 v115, 1.0, v115
	v_rcp_f32_e32 v114, v114
	v_rcp_f32_e32 v115, v115
	s_nop 0
	v_pk_mul_f32 v[112:113], v[112:113], v[114:115]
	s_nop 0
	v_pk_mul_f32 v[106:107], v[106:107], v[112:113]
	v_mul_f32_e32 v112, 0xbfb8aa3b, v108
	v_mul_f32_e32 v113, 0xbfb8aa3b, v109
	v_exp_f32_e32 v112, v112
	v_exp_f32_e32 v113, v113
	v_add_f32_e32 v112, 1.0, v112
	v_add_f32_e32 v113, 1.0, v113
	v_rcp_f32_e32 v112, v112
	v_rcp_f32_e32 v113, v113
	s_nop 0
	v_pk_mul_f32 v[108:109], v[108:109], v[112:113]
	s_nop 0
	v_pk_mul_f32 v[108:109], v[100:101], v[108:109]
	v_pk_mul_f32 v[100:101], v[110:111], v[116:117] op_sel_hi:[1,0]
	v_lshl_add_u64 v[112:113], v[118:119], 0, v[124:125]
	v_mul_f32_e32 v110, 0xbfb8aa3b, v100
	v_mul_f32_e32 v111, 0xbfb8aa3b, v101
	v_exp_f32_e32 v110, v110
	v_exp_f32_e32 v111, v111
	v_add_f32_e32 v110, 1.0, v110
	v_add_f32_e32 v111, 1.0, v111
	v_rcp_f32_e32 v110, v110
	v_rcp_f32_e32 v111, v111
	s_nop 0
	v_pk_mul_f32 v[100:101], v[100:101], v[110:111]
	s_nop 0
	v_pk_mul_f32 v[110:111], v[102:103], v[100:101]
	v_cvt_pk_bf16_f32 v102, v108, v109
	v_or_b32_e32 v108, 32, v142
	v_cvt_pk_bf16_f32 v100, v104, v105
	v_cvt_pk_bf16_f32 v101, v106, v107
	v_cvt_pk_bf16_f32 v103, v110, v111
	global_store_dwordx4 v[112:113], v[100:103], off
	s_nop 1
	v_mov_b32_e32 v100, v238
	v_pk_mul_f32 v[96:97], v[96:97], v[100:101] op_sel_hi:[1,0]
	v_mad_i64_i32 v[102:103], s[0:1], v108, s17, v[140:141]
	v_mul_f32_e32 v101, 0xbfb8aa3b, v96
	v_exp_f32_e32 v101, v101
	s_nop 0
	v_add_f32_e32 v101, 1.0, v101
	v_rcp_f32_e32 v104, v101
	v_pk_mul_f32 v[88:89], v[88:89], v[100:101] op_sel_hi:[1,0]
	v_mul_f32_e32 v101, 0xbfb8aa3b, v97
	v_exp_f32_e32 v101, v101
	s_nop 0
	v_add_f32_e32 v101, 1.0, v101
	v_rcp_f32_e32 v105, v101
	v_pk_mul_f32 v[90:91], v[90:91], v[100:101] op_sel_hi:[1,0]
	v_pk_mul_f32 v[92:93], v[92:93], v[100:101] op_sel_hi:[1,0]
	v_pk_mul_f32 v[84:85], v[84:85], v[100:101] op_sel_hi:[1,0]
	v_pk_mul_f32 v[96:97], v[96:97], v[104:105]
; __device__ __forceinline__ unsigned pk2(float lo, float hi) { return pg8::cvt_pk_bf16(lo, hi); }
; __device__ __forceinline__ float fast_exp2(float x) { return __builtin_amdgcn_exp2f(x); }
; __device__ __forceinline__ float fast_rcp(float x) { return __builtin_amdgcn_rcpf(x); }
;     __device__ __forceinline__ void operator()(const pg8::f32x4 (&acc)[2][2][4][2], const pg8::Unit& u, int wr, int wc, int fr, int fq) const {
;     ...
;             for (int m = 0; m < 4; ++m) {
;                 const int row = row0 + ai * 128 + m * 16; const float rs = rstd_of(ssq, row);
;                 bf16_t* dst = O + (size_t)row * DFF + col0;
;                 float v[8];
; #pragma unroll
;                 for (int n = 0; n < 2; ++n)
; #pragma unroll
;                     for (int j = 0; j < 4; ++j) { const float g = acc[ai][0][m][n][j] * rs, uu = acc[ai][1][m][n][j] * rs; v[n * 4 + j] = g * fast_rcp(1.0f + fast_exp2(-g * LOG2E)) * uu; }
;                 u32x4 w; w.x = pk2(v[0], v[1]); w.y = pk2(v[2], v[3]); w.z = pk2(v[4], v[5]); w.w = pk2(v[6], v[7]);
;                 *(u32x4*)dst = w;
;             }
	v_pk_mul_f32 v[86:87], v[86:87], v[100:101] op_sel_hi:[1,0]
	v_pk_mul_f32 v[88:89], v[88:89], v[96:97]
	v_pk_mul_f32 v[96:97], v[98:99], v[100:101] op_sel_hi:[1,0]
	s_nop 0
	v_mul_f32_e32 v98, 0xbfb8aa3b, v96
	v_mul_f32_e32 v99, 0xbfb8aa3b, v97
	v_exp_f32_e32 v98, v98
	v_exp_f32_e32 v99, v99
	v_add_f32_e32 v98, 1.0, v98
	v_add_f32_e32 v99, 1.0, v99
	v_rcp_f32_e32 v98, v98
	v_rcp_f32_e32 v99, v99
	s_nop 0
	v_pk_mul_f32 v[96:97], v[96:97], v[98:99]
	s_nop 0
	v_pk_mul_f32 v[90:91], v[90:91], v[96:97]
	v_mul_f32_e32 v96, 0xbfb8aa3b, v92
	v_mul_f32_e32 v97, 0xbfb8aa3b, v93
	v_exp_f32_e32 v96, v96
	v_exp_f32_e32 v97, v97
	v_add_f32_e32 v96, 1.0, v96
	v_add_f32_e32 v97, 1.0, v97
	v_rcp_f32_e32 v96, v96
	v_rcp_f32_e32 v97, v97
	s_nop 0
	v_pk_mul_f32 v[92:93], v[92:93], v[96:97]
	s_nop 0
	v_pk_mul_f32 v[92:93], v[84:85], v[92:93]
	v_pk_mul_f32 v[84:85], v[94:95], v[100:101] op_sel_hi:[1,0]
	v_lshl_add_u64 v[96:97], v[102:103], 0, v[124:125]
	v_mul_f32_e32 v94, 0xbfb8aa3b, v84
	v_mul_f32_e32 v95, 0xbfb8aa3b, v85
	v_exp_f32_e32 v94, v94
	v_exp_f32_e32 v95, v95
	v_add_f32_e32 v94, 1.0, v94
	v_add_f32_e32 v95, 1.0, v95
	v_rcp_f32_e32 v94, v94
	v_rcp_f32_e32 v95, v95
	s_nop 0
	v_pk_mul_f32 v[84:85], v[84:85], v[94:95]
	s_nop 0
	v_pk_mul_f32 v[94:95], v[86:87], v[84:85]
	v_cvt_pk_bf16_f32 v86, v92, v93
	v_or_b32_e32 v92, 48, v142
	v_cvt_pk_bf16_f32 v84, v88, v89
	v_cvt_pk_bf16_f32 v85, v90, v91
	v_cvt_pk_bf16_f32 v87, v94, v95
	global_store_dwordx4 v[96:97], v[84:87], off
	s_nop 1
	v_mov_b32_e32 v84, v239
	v_pk_mul_f32 v[80:81], v[80:81], v[84:85] op_sel_hi:[1,0]
	v_mad_i64_i32 v[86:87], s[0:1], v92, s17, v[140:141]
	v_mul_f32_e32 v85, 0xbfb8aa3b, v80
	v_exp_f32_e32 v85, v85
	s_nop 0
	v_add_f32_e32 v85, 1.0, v85
	v_rcp_f32_e32 v88, v85
	v_pk_mul_f32 v[72:73], v[72:73], v[84:85] op_sel_hi:[1,0]
	v_mul_f32_e32 v85, 0xbfb8aa3b, v81
	v_exp_f32_e32 v85, v85
	s_nop 0
	v_add_f32_e32 v85, 1.0, v85
	v_rcp_f32_e32 v89, v85
	v_pk_mul_f32 v[74:75], v[74:75], v[84:85] op_sel_hi:[1,0]
	v_pk_mul_f32 v[76:77], v[76:77], v[84:85] op_sel_hi:[1,0]
	v_pk_mul_f32 v[68:69], v[68:69], v[84:85] op_sel_hi:[1,0]
	v_pk_mul_f32 v[80:81], v[80:81], v[88:89]
	v_pk_mul_f32 v[70:71], v[70:71], v[84:85] op_sel_hi:[1,0]
	v_pk_mul_f32 v[72:73], v[72:73], v[80:81]
	v_pk_mul_f32 v[80:81], v[82:83], v[84:85] op_sel_hi:[1,0]
	s_nop 0
	v_mul_f32_e32 v82, 0xbfb8aa3b, v80
	v_mul_f32_e32 v83, 0xbfb8aa3b, v81
	v_exp_f32_e32 v82, v82
	v_exp_f32_e32 v83, v83
	v_add_f32_e32 v82, 1.0, v82
	v_add_f32_e32 v83, 1.0, v83
	v_rcp_f32_e32 v82, v82
	v_rcp_f32_e32 v83, v83
	s_nop 0
	v_pk_mul_f32 v[80:81], v[80:81], v[82:83]
	s_nop 0
	v_pk_mul_f32 v[74:75], v[74:75], v[80:81]
	v_mul_f32_e32 v80, 0xbfb8aa3b, v76
	v_mul_f32_e32 v81, 0xbfb8aa3b, v77
	v_exp_f32_e32 v80, v80
	v_exp_f32_e32 v81, v81
	v_add_f32_e32 v80, 1.0, v80
	v_add_f32_e32 v81, 1.0, v81
	v_rcp_f32_e32 v80, v80
	v_rcp_f32_e32 v81, v81
	s_nop 0
	v_pk_mul_f32 v[76:77], v[76:77], v[80:81]
	s_nop 0
	v_pk_mul_f32 v[76:77], v[68:69], v[76:77]
	v_pk_mul_f32 v[68:69], v[78:79], v[84:85] op_sel_hi:[1,0]
	v_lshl_add_u64 v[80:81], v[86:87], 0, v[124:125]
	v_mul_f32_e32 v78, 0xbfb8aa3b, v68
	v_mul_f32_e32 v79, 0xbfb8aa3b, v69
	v_exp_f32_e32 v78, v78
	v_exp_f32_e32 v79, v79
	v_add_f32_e32 v78, 1.0, v78
	v_add_f32_e32 v79, 1.0, v79
	v_rcp_f32_e32 v78, v78
	v_rcp_f32_e32 v79, v79
	s_nop 0
	v_pk_mul_f32 v[68:69], v[68:69], v[78:79]
	s_nop 0
	v_pk_mul_f32 v[78:79], v[70:71], v[68:69]
	v_cvt_pk_bf16_f32 v70, v76, v77
	v_add_u32_e32 v76, 0x80, v142
	v_cvt_pk_bf16_f32 v68, v72, v73
	v_cvt_pk_bf16_f32 v69, v74, v75
	v_cvt_pk_bf16_f32 v71, v78, v79
	global_store_dwordx4 v[80:81], v[68:71], off
	s_nop 1
	v_mov_b32_e32 v68, v244
	v_pk_mul_f32 v[64:65], v[64:65], v[68:69] op_sel_hi:[1,0]
	v_mad_i64_i32 v[70:71], s[0:1], v76, s17, v[140:141]
	v_mul_f32_e32 v69, 0xbfb8aa3b, v64
	v_exp_f32_e32 v69, v69
	s_nop 0
	v_add_f32_e32 v69, 1.0, v69
	v_rcp_f32_e32 v72, v69
	v_pk_mul_f32 v[56:57], v[56:57], v[68:69] op_sel_hi:[1,0]
	v_mul_f32_e32 v69, 0xbfb8aa3b, v65
	v_exp_f32_e32 v69, v69
	s_nop 0
	v_add_f32_e32 v69, 1.0, v69
	v_rcp_f32_e32 v73, v69
	v_pk_mul_f32 v[58:59], v[58:59], v[68:69] op_sel_hi:[1,0]
	v_pk_mul_f32 v[60:61], v[60:61], v[68:69] op_sel_hi:[1,0]
	v_pk_mul_f32 v[52:53], v[52:53], v[68:69] op_sel_hi:[1,0]
	v_pk_mul_f32 v[64:65], v[64:65], v[72:73]
	v_pk_mul_f32 v[54:55], v[54:55], v[68:69] op_sel_hi:[1,0]
	v_pk_mul_f32 v[56:57], v[56:57], v[64:65]
	v_pk_mul_f32 v[64:65], v[66:67], v[68:69] op_sel_hi:[1,0]
	s_nop 0
	v_mul_f32_e32 v66, 0xbfb8aa3b, v64
	v_mul_f32_e32 v67, 0xbfb8aa3b, v65
	v_exp_f32_e32 v66, v66
	v_exp_f32_e32 v67, v67
	v_add_f32_e32 v66, 1.0, v66
	v_add_f32_e32 v67, 1.0, v67
	v_rcp_f32_e32 v66, v66
	v_rcp_f32_e32 v67, v67
	s_nop 0
	v_pk_mul_f32 v[64:65], v[64:65], v[66:67]
	s_nop 0
	v_pk_mul_f32 v[58:59], v[58:59], v[64:65]
	v_mul_f32_e32 v64, 0xbfb8aa3b, v60
	v_mul_f32_e32 v65, 0xbfb8aa3b, v61
	v_exp_f32_e32 v64, v64
	v_exp_f32_e32 v65, v65
	v_add_f32_e32 v64, 1.0, v64
	v_add_f32_e32 v65, 1.0, v65
	v_rcp_f32_e32 v64, v64
	v_rcp_f32_e32 v65, v65
	s_nop 0
	v_pk_mul_f32 v[60:61], v[60:61], v[64:65]
	s_nop 0
	v_pk_mul_f32 v[60:61], v[52:53], v[60:61]
	v_pk_mul_f32 v[52:53], v[62:63], v[68:69] op_sel_hi:[1,0]
	v_lshl_add_u64 v[64:65], v[70:71], 0, v[124:125]
	v_mul_f32_e32 v62, 0xbfb8aa3b, v52
	v_mul_f32_e32 v63, 0xbfb8aa3b, v53
	v_exp_f32_e32 v62, v62
	v_exp_f32_e32 v63, v63
	v_add_f32_e32 v62, 1.0, v62
	v_add_f32_e32 v63, 1.0, v63
	v_rcp_f32_e32 v62, v62
	v_rcp_f32_e32 v63, v63
	s_nop 0
	v_pk_mul_f32 v[52:53], v[52:53], v[62:63]
	s_nop 0
	v_pk_mul_f32 v[62:63], v[54:55], v[52:53]
	v_cvt_pk_bf16_f32 v54, v60, v61
	v_add_u32_e32 v60, 0x90, v142
; #define PG8_BAR __builtin_amdgcn_s_barrier()
; __device__ __forceinline__ unsigned pk2(float lo, float hi) { return pg8::cvt_pk_bf16(lo, hi); }
; __device__ __forceinline__ float fast_exp2(float x) { return __builtin_amdgcn_exp2f(x); }
; __device__ __forceinline__ float fast_rcp(float x) { return __builtin_amdgcn_rcpf(x); }
; template <class Epi, class Sched, bool ALIGN_EPI = false, bool SP2 = false>
; __device__ __forceinline__ void gemm_phase(PG8_LAS unsigned char* lds, const Gemm g, const Sched& S, const Epi& E) {
;     ...
;         if constexpr (!Epi::AFTER_DRAIN) { E(acc, cur, wr, wc, fr, fq); S.done(cur); }
;         if (!has_next) break;
; #pragma unroll
;         for (int a = 0; a < 2; ++a)
; #pragma unroll
;             for (int b = 0; b < 2; ++b)
; #pragma unroll
;                 for (int m = 0; m < 4; ++m)
; #pragma unroll
;                     for (int n = 0; n < 2; ++n) acc[a][b][m][n] = (f32x4){0.f, 0.f, 0.f, 0.f};
;         cur = nxt; cA = nA; cB = nB; ++ui;
;         if constexpr (ALIGN_EPI) { if (wr == 1) PG8_BAR; }
;     }
;     __device__ __forceinline__ void operator()(const pg8::f32x4 (&acc)[2][2][4][2], const pg8::Unit& u, int wr, int wc, int fr, int fq) const {
;     ...
;             for (int m = 0; m < 4; ++m) {
;                 const int row = row0 + ai * 128 + m * 16; const float rs = rstd_of(ssq, row);
;                 bf16_t* dst = O + (size_t)row * DFF + col0;
;                 float v[8];
; #pragma unroll
;                 for (int n = 0; n < 2; ++n)
; #pragma unroll
;                     for (int j = 0; j < 4; ++j) { const float g = acc[ai][0][m][n][j] * rs, uu = acc[ai][1][m][n][j] * rs; v[n * 4 + j] = g * fast_rcp(1.0f + fast_exp2(-g * LOG2E)) * uu; }
;                 u32x4 w; w.x = pk2(v[0], v[1]); w.y = pk2(v[2], v[3]); w.z = pk2(v[4], v[5]); w.w = pk2(v[6], v[7]);
;                 *(u32x4*)dst = w;
;             }
	v_cvt_pk_bf16_f32 v52, v56, v57
	v_cvt_pk_bf16_f32 v53, v58, v59
	v_cvt_pk_bf16_f32 v55, v62, v63
	global_store_dwordx4 v[64:65], v[52:55], off
	s_nop 1
	v_mov_b32_e32 v52, v245
	v_pk_mul_f32 v[48:49], v[48:49], v[52:53] op_sel_hi:[1,0]
	v_mad_i64_i32 v[54:55], s[0:1], v60, s17, v[140:141]
	v_mul_f32_e32 v53, 0xbfb8aa3b, v48
	v_exp_f32_e32 v53, v53
	s_nop 0
	v_add_f32_e32 v53, 1.0, v53
	v_rcp_f32_e32 v56, v53
	v_pk_mul_f32 v[40:41], v[40:41], v[52:53] op_sel_hi:[1,0]
	v_mul_f32_e32 v53, 0xbfb8aa3b, v49
	v_exp_f32_e32 v53, v53
	s_nop 0
	v_add_f32_e32 v53, 1.0, v53
	v_rcp_f32_e32 v57, v53
	v_pk_mul_f32 v[42:43], v[42:43], v[52:53] op_sel_hi:[1,0]
	v_pk_mul_f32 v[44:45], v[44:45], v[52:53] op_sel_hi:[1,0]
	v_pk_mul_f32 v[36:37], v[36:37], v[52:53] op_sel_hi:[1,0]
	v_pk_mul_f32 v[48:49], v[48:49], v[56:57]
	v_pk_mul_f32 v[38:39], v[38:39], v[52:53] op_sel_hi:[1,0]
	v_pk_mul_f32 v[40:41], v[40:41], v[48:49]
	v_pk_mul_f32 v[48:49], v[50:51], v[52:53] op_sel_hi:[1,0]
	s_nop 0
	v_mul_f32_e32 v50, 0xbfb8aa3b, v48
	v_mul_f32_e32 v51, 0xbfb8aa3b, v49
	v_exp_f32_e32 v50, v50
	v_exp_f32_e32 v51, v51
	v_add_f32_e32 v50, 1.0, v50
	v_add_f32_e32 v51, 1.0, v51
	v_rcp_f32_e32 v50, v50
	v_rcp_f32_e32 v51, v51
	s_nop 0
	v_pk_mul_f32 v[48:49], v[48:49], v[50:51]
	s_nop 0
	v_pk_mul_f32 v[42:43], v[42:43], v[48:49]
	v_mul_f32_e32 v48, 0xbfb8aa3b, v44
	v_mul_f32_e32 v49, 0xbfb8aa3b, v45
	v_exp_f32_e32 v48, v48
	v_exp_f32_e32 v49, v49
	v_add_f32_e32 v48, 1.0, v48
	v_add_f32_e32 v49, 1.0, v49
	v_rcp_f32_e32 v48, v48
	v_rcp_f32_e32 v49, v49
	s_nop 0
	v_pk_mul_f32 v[44:45], v[44:45], v[48:49]
	s_nop 0
	v_pk_mul_f32 v[44:45], v[36:37], v[44:45]
	v_pk_mul_f32 v[36:37], v[46:47], v[52:53] op_sel_hi:[1,0]
	v_lshl_add_u64 v[48:49], v[54:55], 0, v[124:125]
	v_mul_f32_e32 v46, 0xbfb8aa3b, v36
	v_mul_f32_e32 v47, 0xbfb8aa3b, v37
	v_exp_f32_e32 v46, v46
	v_exp_f32_e32 v47, v47
	v_add_f32_e32 v46, 1.0, v46
	v_add_f32_e32 v47, 1.0, v47
	v_rcp_f32_e32 v46, v46
	v_rcp_f32_e32 v47, v47
	s_nop 0
	v_pk_mul_f32 v[36:37], v[36:37], v[46:47]
	s_nop 0
	v_pk_mul_f32 v[46:47], v[38:39], v[36:37]
	v_cvt_pk_bf16_f32 v38, v44, v45
	v_add_u32_e32 v44, 0xa0, v142
	v_cvt_pk_bf16_f32 v36, v40, v41
	v_cvt_pk_bf16_f32 v37, v42, v43
	v_cvt_pk_bf16_f32 v39, v46, v47
	global_store_dwordx4 v[48:49], v[36:39], off
	s_nop 1
	v_mov_b32_e32 v36, v246
	v_pk_mul_f32 v[28:29], v[28:29], v[36:37] op_sel_hi:[1,0]
	v_mad_i64_i32 v[38:39], s[0:1], v44, s17, v[140:141]
	v_mul_f32_e32 v37, 0xbfb8aa3b, v28
	v_exp_f32_e32 v37, v37
	s_nop 0
	v_add_f32_e32 v37, 1.0, v37
	v_rcp_f32_e32 v40, v37
	v_pk_mul_f32 v[20:21], v[20:21], v[36:37] op_sel_hi:[1,0]
	v_mul_f32_e32 v37, 0xbfb8aa3b, v29
	v_exp_f32_e32 v37, v37
	s_nop 0
	v_add_f32_e32 v37, 1.0, v37
	v_rcp_f32_e32 v41, v37
	v_pk_mul_f32 v[22:23], v[22:23], v[36:37] op_sel_hi:[1,0]
	v_pk_mul_f32 v[24:25], v[24:25], v[36:37] op_sel_hi:[1,0]
	v_pk_mul_f32 v[16:17], v[16:17], v[36:37] op_sel_hi:[1,0]
	v_pk_mul_f32 v[28:29], v[28:29], v[40:41]
	v_pk_mul_f32 v[18:19], v[18:19], v[36:37] op_sel_hi:[1,0]
	v_pk_mul_f32 v[20:21], v[20:21], v[28:29]
	v_pk_mul_f32 v[28:29], v[30:31], v[36:37] op_sel_hi:[1,0]
	s_nop 0
	v_mul_f32_e32 v30, 0xbfb8aa3b, v28
	v_mul_f32_e32 v31, 0xbfb8aa3b, v29
	v_exp_f32_e32 v30, v30
	v_exp_f32_e32 v31, v31
	v_add_f32_e32 v30, 1.0, v30
	v_add_f32_e32 v31, 1.0, v31
	v_rcp_f32_e32 v30, v30
	v_rcp_f32_e32 v31, v31
	s_nop 0
	v_pk_mul_f32 v[28:29], v[28:29], v[30:31]
	s_nop 0
	v_pk_mul_f32 v[22:23], v[22:23], v[28:29]
	v_mul_f32_e32 v28, 0xbfb8aa3b, v24
	v_mul_f32_e32 v29, 0xbfb8aa3b, v25
	v_exp_f32_e32 v28, v28
	v_exp_f32_e32 v29, v29
	v_add_f32_e32 v28, 1.0, v28
	v_add_f32_e32 v29, 1.0, v29
	v_rcp_f32_e32 v28, v28
	v_rcp_f32_e32 v29, v29
	s_nop 0
	v_pk_mul_f32 v[24:25], v[24:25], v[28:29]
	s_nop 0
	v_pk_mul_f32 v[24:25], v[16:17], v[24:25]
	v_pk_mul_f32 v[16:17], v[26:27], v[36:37] op_sel_hi:[1,0]
	v_lshl_add_u64 v[28:29], v[38:39], 0, v[124:125]
	v_mul_f32_e32 v26, 0xbfb8aa3b, v16
	v_mul_f32_e32 v27, 0xbfb8aa3b, v17
	v_exp_f32_e32 v26, v26
	v_exp_f32_e32 v27, v27
	v_add_f32_e32 v26, 1.0, v26
	v_add_f32_e32 v27, 1.0, v27
	v_rcp_f32_e32 v26, v26
	v_rcp_f32_e32 v27, v27
	s_nop 0
	v_pk_mul_f32 v[16:17], v[16:17], v[26:27]
	s_nop 0
	v_pk_mul_f32 v[26:27], v[18:19], v[16:17]
	v_cvt_pk_bf16_f32 v18, v24, v25
	v_add_u32_e32 v24, 0xb0, v142
	v_cvt_pk_bf16_f32 v16, v20, v21
	v_cvt_pk_bf16_f32 v17, v22, v23
	v_cvt_pk_bf16_f32 v19, v26, v27
	global_store_dwordx4 v[28:29], v[16:19], off
	s_nop 1
	v_mov_b32_e32 v16, v247
	v_pk_mul_f32 v[12:13], v[12:13], v[16:17] op_sel_hi:[1,0]
	v_mad_i64_i32 v[18:19], s[0:1], v24, s17, v[140:141]
	v_mul_f32_e32 v17, 0xbfb8aa3b, v12
	v_exp_f32_e32 v17, v17
	s_mov_b64 s[0:1], -1
	s_andn2_b64 vcc, exec, s[38:39]
	v_add_f32_e32 v17, 1.0, v17
	v_rcp_f32_e32 v20, v17
	v_pk_mul_f32 v[4:5], v[4:5], v[16:17] op_sel_hi:[1,0]
	v_mul_f32_e32 v17, 0xbfb8aa3b, v13
	v_exp_f32_e32 v17, v17
	s_nop 0
	v_add_f32_e32 v17, 1.0, v17
	v_rcp_f32_e32 v21, v17
	v_pk_mul_f32 v[6:7], v[6:7], v[16:17] op_sel_hi:[1,0]
	v_pk_mul_f32 v[8:9], v[8:9], v[16:17] op_sel_hi:[1,0]
	v_pk_mul_f32 v[0:1], v[0:1], v[16:17] op_sel_hi:[1,0]
	v_pk_mul_f32 v[12:13], v[12:13], v[20:21]
	v_pk_mul_f32 v[2:3], v[2:3], v[16:17] op_sel_hi:[1,0]
	v_pk_mul_f32 v[4:5], v[4:5], v[12:13]
	v_pk_mul_f32 v[12:13], v[14:15], v[16:17] op_sel_hi:[1,0]
	s_nop 0
	v_mul_f32_e32 v14, 0xbfb8aa3b, v12
	v_mul_f32_e32 v15, 0xbfb8aa3b, v13
	v_exp_f32_e32 v14, v14
	v_exp_f32_e32 v15, v15
	v_add_f32_e32 v14, 1.0, v14
	v_add_f32_e32 v15, 1.0, v15
	v_rcp_f32_e32 v14, v14
	v_rcp_f32_e32 v15, v15
	s_nop 0
	v_pk_mul_f32 v[12:13], v[12:13], v[14:15]
	s_nop 0
	v_pk_mul_f32 v[6:7], v[6:7], v[12:13]
	v_mul_f32_e32 v12, 0xbfb8aa3b, v8
	v_mul_f32_e32 v13, 0xbfb8aa3b, v9
	v_exp_f32_e32 v12, v12
	v_exp_f32_e32 v13, v13
	v_add_f32_e32 v12, 1.0, v12
	v_add_f32_e32 v13, 1.0, v13
	v_rcp_f32_e32 v12, v12
	v_rcp_f32_e32 v13, v13
	s_nop 0
	v_pk_mul_f32 v[8:9], v[8:9], v[12:13]
	s_nop 0
	v_pk_mul_f32 v[8:9], v[0:1], v[8:9]
	v_pk_mul_f32 v[0:1], v[10:11], v[16:17] op_sel_hi:[1,0]
	v_lshl_add_u64 v[12:13], v[18:19], 0, v[124:125]
	v_mul_f32_e32 v10, 0xbfb8aa3b, v0
	v_mul_f32_e32 v11, 0xbfb8aa3b, v1
	v_exp_f32_e32 v10, v10
	v_exp_f32_e32 v11, v11
	v_add_f32_e32 v10, 1.0, v10
	v_add_f32_e32 v11, 1.0, v11
	v_rcp_f32_e32 v10, v10
	v_rcp_f32_e32 v11, v11
	s_nop 0
	v_pk_mul_f32 v[0:1], v[0:1], v[10:11]
	s_nop 0
	v_pk_mul_f32 v[10:11], v[2:3], v[0:1]
	v_cvt_pk_bf16_f32 v0, v4, v5
	v_cvt_pk_bf16_f32 v1, v6, v7
	v_cvt_pk_bf16_f32 v2, v8, v9
	v_cvt_pk_bf16_f32 v3, v10, v11
	global_store_dwordx4 v[12:13], v[0:3], off
	s_cbranch_vccnz .LBB0_619
	s_andn2_b64 vcc, exec, s[4:5]
	s_cbranch_vccnz .LBB0_618
	s_barrier
	s_branch .LBB0_618
